# LRU conv-tile cache: fwd pass publishes bf16 conv tiles (4 strips of a head share them via a counter hand-off), bwd pass loads them instead of recomputing
# speedup vs baseline: 1.0104x; 1.0020x over previous
; #define LAS __attribute__((address_space(3)))
; #define LDS_BARRIER() do { asm volatile("s_waitcnt lgkmcnt(0)" ::: "memory"); __builtin_amdgcn_s_barrier(); asm volatile("" ::: "memory"); } while (0)
; template <int dir>
; __device__ __forceinline__ void lru_pass(LAS unsigned char* lds, const Params& P, int b, int h, int q, bool dry) {
;     ...
;         LDS_BARRIER();
;         if (dir == 0) {
; #pragma unroll
;             for (int i = 0; i < 4; ++i) { const int id = tid + i * NTHREADS; *(u32x4*)(Hg + (size_t)(t0_prev + (id >> 3)) * DM + (id & 7) * 4) = *(const LAS u32x4*)(TOUT + (id >> 3) * IO_WP + (id & 7) * 16); }
;         } else if (!dry) {
; #pragma unroll
;             for (int i = 0; i < 2; ++i) { const int id = tid + i * NTHREADS; *(u32x4*)(Z + ZSLAB(8 + h, (size_t)b * SEQ + t0_prev + (id >> 2)) + q * 32 + (id & 3) * 8) = *(const LAS u32x4*)(TOUT + (id >> 2) * IO_NP + (id & 3) * 16); }
;         }
.LBB0_277:
	s_add_u32 s40, s22, 0x7400000
	s_addc_u32 s41, s23, 0
	s_cmp_lg_u32 s101, 0
	s_cbranch_scc1 .Lpp_b_noy
	s_barrier

; #define LAS __attribute__((address_space(3)))
; __device__ __forceinline__ int opaque_tid() { int t = threadIdx.x; asm volatile("" : "+v"(t)); return t; }
; #define LDS_BARRIER() do { asm volatile("s_waitcnt lgkmcnt(0)" ::: "memory"); __builtin_amdgcn_s_barrier(); asm volatile("" ::: "memory"); } while (0)
; template <int dir>
; __device__ __forceinline__ void lru_pass(LAS unsigned char* lds, const Params& P, int b, int h, int q, bool dry) {
;     ...
;     {
; #pragma unroll
;         for (int i = 0; i < 2; ++i) { const int idx = tid + i * NTHREADS, gate = idx >> 9, n = (idx >> 4) & 31, kc = idx & 15;
;             *(LAS u32x4*)(WB + (gate * 32 + n) * XC_PITCH + kc * 16) = *(const u32x4*)(LruW + ((size_t)((dir * 2 + gate) * 8 + h) * 128 + q * 32 + n) * 128 + kc * 8); }
;         const float br = -LOG2E * P.lru_ba[(dir * 8 + h) * 128 + chl], bi = -LOG2E * P.lru_bx[(dir * 8 + h) * 128 + chl];
;         const float lam = P.lru_lambda[dir * 1024 + ch];
;         const float cl = -8.0f * LOG2E * log1pf(__expf(-lam));
;         float carry = 0.f;
;         LruTile cur = lru_tile(Z, ZC, b, h, dir, 0);
;         u32x4 rows[11];
;         constexpr int NIN = dir == 0 ? 2 : 4;
;         u32x4 inr[NIN];
;         lru_load_rows(rows, cur, tr, cgp);
; __device__ __forceinline__ void lru_strip(LAS unsigned char* lds, const Params& P, int strip, bool dry) {
;     const int tid = opaque_tid();
;     const int b = strip >> 5, h = (strip >> 2) & 7, q = strip & 3;
;     LAS float* CWL = (LAS float*)(lds + 256 * XC_PITCH + 2048 + 64 * XC_PITCH);
;     for (int i = tid; i < 640; i += NTHREADS) { const int k = i >> 7, c = i & 127; CWL[i] = k < 4 ? P.conv_w[k * 1024 + h * 128 + c] : P.conv_b[h * 128 + c]; }
;     LDS_BARRIER();
;     lru_pass<0>(lds, P, b, h, q, dry);
.LBB0_278:
	s_ashr_i32 s25, s2, 3
	v_mov_b32_e32 v128, v167
	s_bfe_u32 s26, s25, 0x30002
	s_lshl_b32 s27, s26, 7
	v_and_b32_e32 v204, 0x7f, v128
	v_or_b32_e32 v204, s27, v204
	v_lshrrev_b32_e32 v205, 7, v128
	v_lshl_or_b32 v205, v205, 10, v204
	v_lshlrev_b32_e32 v205, 2, v205
	v_lshlrev_b32_e32 v204, 2, v204
	global_load_dword v205, v205, s[52:53]
	global_load_dword v204, v204, s[54:55]
	v_readlane_b32 s0, v255, 19
	s_nop 3
	v_lshl_add_u32 v206, v128, 2, s0
	v_mov_b32_e32 v12, v167
	s_lshl_b32 s0, s25, 5
	s_and_b32 s28, s0, 0x60
	v_and_b32_e32 v15, 31, v12
	v_or_b32_e32 v17, s28, v15
	v_add_u32_e32 v14, 0x200, v12
	v_or_b32_e32 v11, s27, v17
	v_ashrrev_i32_e32 v8, 9, v12
	v_ashrrev_i32_e32 v10, 9, v14
	v_lshlrev_b32_e32 v16, 2, v11
	v_and_b32_e32 v13, 15, v12
	v_lshl_or_b32 v2, v8, 3, s26
	v_lshl_or_b32 v6, v10, 3, s26
	global_load_dword v18, v16, s[64:65]
	v_bfe_u32 v9, v12, 4, 5
	v_lshlrev_b32_e32 v64, 4, v13
	v_ashrrev_i32_e32 v3, 31, v2
	v_ashrrev_i32_e32 v7, 31, v6
	v_or_b32_e32 v4, s28, v9
	v_lshl_add_u64 v[0:1], s[38:39], 0, v[64:65]
	v_lshlrev_b64 v[2:3], 15, v[2:3]
	v_lshlrev_b64 v[6:7], 15, v[6:7]
	v_lshlrev_b32_e32 v4, 8, v4
	v_mov_b32_e32 v5, v65
	v_lshl_add_u64 v[2:3], v[0:1], 0, v[2:3]
	v_lshl_add_u64 v[0:1], v[0:1], 0, v[6:7]
	v_lshl_add_u64 v[2:3], v[2:3], 0, v[4:5]
	v_lshl_add_u64 v[4:5], v[0:1], 0, v[4:5]
	global_load_dwordx4 v[0:3], v[2:3], off
	s_nop 0
	global_load_dwordx4 v[4:7], v[4:5], off
	v_lshlrev_b32_e32 v11, 2, v12
	v_lshl_or_b32 v21, v8, 5, v9
	v_add_u32_e32 v8, s88, v64
	v_lshl_or_b32 v9, v10, 5, v9
	v_and_b32_e32 v22, 16, v11
	v_mad_u64_u32 v[10:11], s[4:5], v21, s89, v[8:9]
	v_mad_u64_u32 v[8:9], s[4:5], v9, s89, v[8:9]
	global_load_dword v9, v16, s[58:59]
	global_load_dword v11, v16, s[62:63]
	s_lshl_b32 s0, s2, 5
	s_and_b32 s0, s0, 0xe0
	s_or_b32 s1, s0, s25
	s_ashr_i32 s78, s1, 5
	s_ashr_i32 s79, s78, 31
	s_lshl_b32 s20, s26, 22
	s_lshl_b64 s[18:19], s[78:79], 19
	s_lshl_b64 s[44:45], s[78:79], 23
	v_readlane_b32 s1, v255, 18
	s_add_u32 s1, s1, s44
	s_addc_u32 s4, s33, s45
	s_lshl_b32 s5, s27, 2
	s_add_u32 s1, s1, s5
	s_addc_u32 s4, s4, 0
	s_add_u32 s5, s68, s18
	s_addc_u32 s6, s69, s19
	s_lshl_b32 s7, s27, 1
	s_add_u32 s48, s5, s7
	s_addc_u32 s49, s6, 0
	s_add_u32 s50, s48, 0x1000
	s_addc_u32 s51, s49, 0
	s_add_u32 s56, s48, 0x1800
	s_addc_u32 s57, s49, 0
	s_add_u32 s60, s48, 0x2000
	s_addc_u32 s61, s49, 0
	s_add_u32 s66, s48, 0x2800
	s_addc_u32 s67, s49, 0
	s_add_u32 s70, s48, 0x3000
	s_addc_u32 s71, s49, 0
	v_ashrrev_i32_e32 v36, 4, v12
	v_lshlrev_b32_e32 v37, 3, v13
	s_add_u32 s72, s48, 0x3800
	s_addc_u32 s73, s49, 0
	s_add_u32 s74, s48, 0x4000
	s_addc_u32 s75, s49, 0
	s_add_u32 s76, s48, 0x4800
	s_addc_u32 s77, s49, 0
	v_readfirstlane_b32 s0, v12
	s_ashr_i32 s6, s0, 6
	s_lshl_b32 s5, s28, 2
	s_add_u32 s8, s1, s5
	v_bfe_u32 v19, v12, 5, 1
	v_lshrrev_b32_e32 v20, 1, v12
	v_and_b32_e32 v33, 3, v12
	s_addc_u32 s9, s4, 0
	v_lshl_or_b32 v110, v36, 13, v37
	v_mov_b32_e32 v111, v65
	v_lshlrev_b64 v[110:111], 1, v[110:111]
	v_lshl_add_u64 v[108:109], s[48:49], 0, v[110:111]
	global_load_dwordx4 v[68:71], v[108:109], off offset:-2048
	global_load_dwordx4 v[72:75], v[108:109], off
	global_load_dwordx4 v[76:79], v[108:109], off offset:2048
	v_lshl_add_u64 v[108:109], s[50:51], 0, v[110:111]
	global_load_dwordx4 v[80:83], v[108:109], off
	v_lshl_add_u64 v[108:109], s[56:57], 0, v[110:111]
	global_load_dwordx4 v[84:87], v[108:109], off
	v_lshl_add_u64 v[108:109], s[60:61], 0, v[110:111]
	global_load_dwordx4 v[88:91], v[108:109], off
	v_lshl_add_u64 v[108:109], s[66:67], 0, v[110:111]
	global_load_dwordx4 v[92:95], v[108:109], off
	v_lshl_add_u64 v[108:109], s[70:71], 0, v[110:111]
	global_load_dwordx4 v[96:99], v[108:109], off
	v_lshl_add_u64 v[108:109], s[72:73], 0, v[110:111]
	global_load_dwordx4 v[100:103], v[108:109], off
	v_lshl_add_u64 v[108:109], s[74:75], 0, v[110:111]
	global_load_dwordx4 v[104:107], v[108:109], off
	v_lshl_add_u64 v[108:109], s[76:77], 0, v[110:111]
	global_load_dwordx4 v[108:111], v[108:109], off
	s_waitcnt vmcnt(14)
	ds_write_b128 v10, v[0:3]
	s_waitcnt vmcnt(13)
	ds_write_b128 v8, v[4:7]
	ds_write_b32 v206, v205
	v_cmp_gt_u32_e32 vcc, 0x80, v128
	s_and_saveexec_b64 s[14:15], vcc
	ds_write_b32 v206, v204 offset:2048
	s_or_b64 exec, exec, s[14:15]
	v_mul_f32_e32 v16, 0xbfb8aa3b, v18
	v_exp_f32_e32 v16, v16
	s_lshl_b32 s1, s6, 5
	s_and_b32 s0, s0, 0x3fffffc0
	v_add_u32_e32 v39, 0, v64
	v_add_f32_e32 v2, 1.0, v16
	v_add_f32_e32 v3, -1.0, v2
	v_frexp_mant_f32_e32 v4, v2
	v_cvt_f64_f32_e32 v[0:1], v2
	v_sub_f32_e32 v5, v3, v2
	v_frexp_exp_i32_f64_e32 v0, v[0:1]
	v_cmp_gt_f32_e32 vcc, s80, v4
	v_sub_f32_e32 v3, v16, v3
	v_add_f32_e32 v1, 1.0, v5
	v_subbrev_co_u32_e32 v0, vcc, 0, v0, vcc
	v_add_f32_e32 v1, v3, v1
	v_sub_u32_e32 v3, 0, v0
	v_ldexp_f32 v2, v2, v3
	v_ldexp_f32 v1, v1, v3
	v_add_f32_e32 v3, -1.0, v2
	v_add_f32_e32 v4, 1.0, v2
	v_add_f32_e32 v5, 1.0, v3
	v_add_f32_e32 v6, -1.0, v4
	v_sub_f32_e32 v5, v2, v5
	v_sub_f32_e32 v2, v2, v6
	v_add_f32_e32 v5, v1, v5
	v_add_f32_e32 v1, v1, v2
	v_add_f32_e32 v6, v4, v1
	v_rcp_f32_e32 v7, v6
	v_add_f32_e32 v2, v3, v5
	v_sub_f32_e32 v4, v6, v4
	v_sub_f32_e32 v3, v2, v3
	v_sub_f32_e32 v1, v1, v4
	v_mul_f32_e32 v4, v2, v7
	v_sub_f32_e32 v3, v5, v3
	v_mul_f32_e32 v5, v6, v4
	v_fma_f32 v8, v4, v6, -v5
	v_fmac_f32_e32 v8, v4, v1
	v_add_f32_e32 v10, v5, v8
	v_sub_f32_e32 v18, v2, v10
	v_sub_f32_e32 v2, v2, v18
	v_sub_f32_e32 v5, v10, v5
	v_sub_f32_e32 v2, v2, v10
	v_sub_f32_e32 v5, v5, v8
	v_add_f32_e32 v2, v3, v2
	v_add_f32_e32 v2, v5, v2
	v_add_f32_e32 v3, v18, v2
	v_mul_f32_e32 v5, v7, v3
	v_mul_f32_e32 v10, v6, v5
	v_fma_f32 v6, v5, v6, -v10
; template <int dir>
; __device__ __forceinline__ void lru_pass(LAS unsigned char* lds, const Params& P, int b, int h, int q, bool dry) {
;     ...
;         const float br = -LOG2E * P.lru_ba[(dir * 8 + h) * 128 + chl], bi = -LOG2E * P.lru_bx[(dir * 8 + h) * 128 + chl];
;         const float lam = P.lru_lambda[dir * 1024 + ch];
;         const float cl = -8.0f * LOG2E * log1pf(__expf(-lam));
;         float carry = 0.f;
;         LruTile cur = lru_tile(Z, ZC, b, h, dir, 0);
;         u32x4 rows[11];
;         constexpr int NIN = dir == 0 ? 2 : 4;
;         u32x4 inr[NIN];
;         lru_load_rows(rows, cur, tr, cgp);
; #pragma unroll
;         for (int i = 0; i < NIN; ++i) inr[i] = (u32x4){0u, 0u, 0u, 0u};
;         int t0_prev = 0;
	v_fmac_f32_e32 v6, v5, v1
	v_add_f32_e32 v1, v10, v6
	v_sub_f32_e32 v8, v18, v3
	v_sub_f32_e32 v18, v3, v1
	v_sub_f32_e32 v3, v3, v18
	v_add_f32_e32 v2, v2, v8
	v_sub_f32_e32 v10, v1, v10
	v_sub_f32_e32 v1, v3, v1
	v_sub_f32_e32 v6, v10, v6
	v_add_f32_e32 v1, v2, v1
	v_cvt_f32_i32_e32 v0, v0
	v_add_f32_e32 v8, v4, v5
	v_add_f32_e32 v1, v6, v1
	v_add_f32_e32 v1, v18, v1
	v_sub_f32_e32 v2, v8, v4
	v_mul_f32_e32 v1, v7, v1
	v_sub_f32_e32 v2, v5, v2
	v_add_f32_e32 v1, v2, v1
	v_mul_f32_e32 v5, 0x3f317218, v0
	v_add_f32_e32 v2, v8, v1
	v_fma_f32 v6, v0, s81, -v5
	v_fmac_f32_e32 v6, 0xb102e308, v0
	v_sub_f32_e32 v0, v2, v8
	v_mul_f32_e32 v3, v2, v2
	v_sub_f32_e32 v0, v1, v0
	v_add_f32_e32 v1, v5, v6
	v_fmamk_f32 v4, v3, 0x3e9b6dac, v200
	v_sub_f32_e32 v5, v1, v5
	v_fmaak_f32 v4, v3, v4, 0x3f2aaada
	v_sub_f32_e32 v5, v6, v5
	v_ldexp_f32 v6, v2, 1
	v_mul_f32_e32 v2, v2, v3
	v_mul_f32_e32 v2, v2, v4
	v_add_f32_e32 v3, v6, v2
	v_sub_f32_e32 v4, v3, v6
	v_ldexp_f32 v0, v0, 1
	v_sub_f32_e32 v2, v2, v4
	v_add_f32_e32 v0, v0, v2
	v_add_f32_e32 v2, v3, v0
	v_sub_f32_e32 v3, v2, v3
	v_sub_f32_e32 v0, v0, v3
	v_add_f32_e32 v3, v1, v2
	v_sub_f32_e32 v4, v3, v1
	v_sub_f32_e32 v6, v3, v4
	v_sub_f32_e32 v1, v1, v6
	v_sub_f32_e32 v2, v2, v4
	v_add_f32_e32 v1, v2, v1
	v_add_f32_e32 v2, v5, v0
	v_sub_f32_e32 v4, v2, v5
	v_add_f32_e32 v1, v2, v1
	v_sub_f32_e32 v6, v2, v4
	v_add_f32_e32 v2, v3, v1
	v_sub_f32_e32 v5, v5, v6
	v_sub_f32_e32 v0, v0, v4
	v_sub_f32_e32 v3, v2, v3
	v_add_f32_e32 v0, v0, v5
	v_sub_f32_e32 v1, v1, v3
	v_add_f32_e32 v0, v0, v1
	v_add_f32_e32 v0, v2, v0
	v_cmp_neq_f32_e32 vcc, s91, v16
	v_mov_b32_e32 v1, v65
	v_lshlrev_b32_e32 v41, 4, v19
	v_cndmask_b32_e32 v0, v201, v0, vcc
	v_cmp_ngt_f32_e32 vcc, -1.0, v16
	s_cmp_eq_u32 s6, 7
	v_or_b32_e32 v35, s1, v41
	v_cndmask_b32_e32 v0, v202, v0, vcc
	v_cmp_neq_f32_e32 vcc, -1.0, v16
	v_ashrrev_i32_e32 v32, 2, v12
	v_ashrrev_i32_e32 v34, 2, v14
	v_cndmask_b32_e32 v0, v203, v0, vcc
	v_cmp_lt_f32_e64 vcc, |v16|, s92
	v_lshlrev_b32_e32 v53, 4, v33
	v_mul_lo_u32 v48, v32, s87
	v_cndmask_b32_e32 v6, v0, v16, vcc
	v_lshlrev_b32_e32 v1, 2, v15
	v_lshlrev_b32_e32 v2, 4, v12
	v_add_u32_e32 v140, s94, v1
	v_and_b32_e32 v3, 48, v2
	v_and_b32_e32 v64, 0x70, v2
	v_and_or_b32 v2, v20, 12, v33
	v_or3_b32 v2, v2, v22, s1
	v_lshl_add_u32 v147, s0, 2, v140
	s_cselect_b64 s[0:1], -1, 0
	s_cmp_eq_u32 s6, 6
	s_cselect_b64 s[16:17], -1, 0
	s_cmp_eq_u32 s6, 5
	s_cselect_b64 s[4:5], -1, 0
	s_cmp_eq_u32 s6, 4
	v_lshl_add_u64 v[130:131], s[8:9], 0, v[64:65]
	s_cselect_b64 s[8:9], -1, 0
	s_cmp_eq_u32 s6, 3
	s_cselect_b64 s[10:11], -1, 0
	s_cmp_eq_u32 s6, 2
	s_cselect_b64 s[12:13], -1, 0
	s_cmp_eq_u32 s6, 1
	s_cselect_b64 s[14:15], -1, 0
	s_add_u32 s46, s20, s18
	s_addc_u32 s47, 0, s19
	s_lshl_b32 s6, s2, 3
	v_ashrrev_i32_e32 v33, 31, v32
	v_mul_lo_u32 v50, v35, s89
	v_mul_lo_u32 v51, v35, s87
	v_mul_lo_u32 v52, v35, s30
	v_ashrrev_i32_e32 v35, 31, v34
	s_bfe_u32 s29, s2, 0x20003
	s_and_b32 s6, s6, 0xc0
	v_lshlrev_b64 v[32:33], 8, v[32:33]
	v_mul_lo_u32 v2, v2, s89
	v_add_u32_e32 v46, s96, v1
	v_mul_lo_u32 v49, v34, s87
	v_add_u32_e32 v1, 0x400, v12
	v_lshlrev_b64 v[34:35], 8, v[34:35]
	v_lshl_add_u64 v[32:33], s[46:47], 0, v[32:33]
	s_add_u32 s18, s82, s46
	v_lshlrev_b32_e32 v38, 5, v13
	v_add_u32_e32 v129, s96, v64
	v_add_u32_e32 v42, 0, v2
	v_mov_b32_e32 v2, s88
	v_ashrrev_i32_e32 v143, 3, v1
	v_add_u32_e32 v1, 0x600, v12
	v_lshl_add_u64 v[34:35], s[46:47], 0, v[34:35]
	v_or3_b32 v32, v32, s6, v53
	v_lshl_or_b32 v64, v36, 10, v37
	s_addc_u32 s19, s83, s47
	v_mov_b32_e32 v66, v65
	v_mov_b32_e32 v67, v65
	s_waitcnt vmcnt(12)
	v_mul_f32_e32 v0, 0xbfb8aa3b, v9
	s_waitcnt vmcnt(11)
	v_mul_f32_e32 v16, 0xbfb8aa3b, v11
	v_add_u32_e32 v40, s95, v3
	v_mad_u32_u24 v43, v15, s89, v2
	v_lshl_add_u32 v44, v17, 1, 0
	v_lshl_add_u32 v45, v15, 1, s95
	v_mul_lo_u32 v47, v36, s93
	v_ashrrev_i32_e32 v148, 3, v12
	v_ashrrev_i32_e32 v145, 3, v14
	v_ashrrev_i32_e32 v141, 3, v1
	v_or3_b32 v34, v34, s6, v53
	v_lshl_add_u64 v[134:135], s[40:41], 0, v[32:33]
	v_lshl_add_u64 v[136:137], v[64:65], 1, s[18:19]
	v_mov_b32_e32 v64, v65
	v_add_u32_e32 v32, 0, v38
	v_mov_b64_e32 v[114:115], v[66:67]
	v_mov_b64_e32 v[118:119], v[66:67]
	s_mov_b32 s90, 0
	v_mul_f32_e32 v138, 0xc138aa3b, v6
	v_lshl_add_u32 v139, v36, 3, -1
	v_cmp_eq_u32_e32 vcc, 0, v19
	v_mul_lo_u32 v149, v148, s30
	v_mul_lo_u32 v146, v145, s30
	v_mul_lo_u32 v144, v143, s30
	v_mul_lo_u32 v142, v141, s30
	v_mov_b32_e32 v1, v0
	v_mov_b32_e32 v2, v0
	v_mov_b32_e32 v3, v0
	v_mov_b32_e32 v4, v0
	v_mov_b32_e32 v5, v0
	v_mov_b32_e32 v6, v0
	v_mov_b32_e32 v7, v0
	v_mov_b32_e32 v8, v0
	v_mov_b32_e32 v9, v0
	v_mov_b32_e32 v10, v0
	v_mov_b32_e32 v11, v0
	v_mov_b32_e32 v12, v0
	v_mov_b32_e32 v13, v0
	v_mov_b32_e32 v14, v0
	v_mov_b32_e32 v15, v0
	v_mov_b32_e32 v17, v16
	v_mov_b32_e32 v18, v16
	v_mov_b32_e32 v19, v16
	v_mov_b32_e32 v20, v16
	v_mov_b32_e32 v21, v16
	v_mov_b32_e32 v22, v16
	v_mov_b32_e32 v23, v16
	v_mov_b32_e32 v24, v16
	v_mov_b32_e32 v25, v16
	v_mov_b32_e32 v26, v16
	v_mov_b32_e32 v27, v16
	v_mov_b32_e32 v28, v16
	v_mov_b32_e32 v29, v16
	v_mov_b32_e32 v30, v16
	v_mov_b32_e32 v31, v16
	v_lshl_add_u64 v[132:133], s[40:41], 0, v[34:35]
	s_movk_i32 s92, 0x100
	v_mov_b32_e32 v165, 0
	s_mov_b64 s[80:81], 0
	v_add_u32_e32 v150, 0x15c00, v32
	v_add_u32_e32 v151, v39, v47
	v_add_u32_e32 v158, v40, v48
	v_add_u32_e32 v159, v40, v49
	v_add_u32_e32 v160, v42, v41
	v_add_u32_e32 v161, v43, v41
	v_add_u32_e32 v162, v44, v50
	v_add_u32_e32 v163, v45, v51
	v_add_u32_e32 v164, v46, v52
	v_mov_b64_e32 v[112:113], v[64:65]
	v_mov_b64_e32 v[116:117], v[64:65]
	s_mov_b32 s91, 0
	s_mov_b32 s93, 0
	s_mov_b32 s97, 0
; #define LAS __attribute__((address_space(3)))
; __device__ __forceinline__ int opaque_tid() { int t = threadIdx.x; asm volatile("" : "+v"(t)); return t; }
; #define LDS_BARRIER() do { asm volatile("s_waitcnt lgkmcnt(0)" ::: "memory"); __builtin_amdgcn_s_barrier(); asm volatile("" ::: "memory"); } while (0)
; template <int dir>
; __device__ __forceinline__ void lru_pass(LAS unsigned char* lds, const Params& P, int b, int h, int q, bool dry) {
;     ...
;             const float Po = __shfl_xor(Pp, 32), Eo = __shfl_xor(E, 32);
;             const float P0 = g ? Po : Pp, E0 = g ? Eo : E, P1 = g ? Pp : Po, E1 = g ? E : Eo;
;             if (g == 0) { AGG[(wid * 2 + 0) * 32 + nl] = P0 * P1; AGG[(wid * 2 + 1) * 32 + nl] = fmaf(P1, E0, E1); }
;             LDS_BARRIER();
;             float cin = carry, cend = carry;
; #pragma unroll
;             for (int w = 0; w < 8; ++w) { const float pw = AGG[(w * 2 + 0) * 32 + nl], ew = AGG[(w * 2 + 1) * 32 + nl]; if (w == wid) cin = cend; cend = fmaf(pw, cend, ew); }
; __device__ __forceinline__ void lru_strip(LAS unsigned char* lds, const Params& P, int strip, bool dry) {
;     const int tid = opaque_tid();
;     const int b = strip >> 5, h = (strip >> 2) & 7, q = strip & 3;
	v_lshrrev_b32_e32 v254, 8, v167
	v_mul_u32_u24_e32 v252, 0x1400, v254
	v_add_u32_e32 v158, v158, v252
	v_add_u32_e32 v159, v159, v252
	v_add_u32_e32 v159, 0xffffec00, v159
	v_lshlrev_b32_e32 v252, 14, v254
	v_mov_b32_e32 v253, 0
	v_lshl_add_u64 v[134:135], v[252:253], 0, v[134:135]
	v_lshl_add_u64 v[132:133], v[252:253], 0, v[132:133]
	s_mov_b32 s18, 0xffffc000
	s_mov_b32 s19, -1
	v_lshl_add_u64 v[132:133], v[132:133], 0, s[18:19]
	v_mul_u32_u24_e32 v252, 0x3600, v254
	v_add_u32_e32 v149, v149, v252
	v_add_u32_e32 v146, v146, v252
	v_add_u32_e32 v144, v144, v252
	v_add_u32_e32 v142, v142, v252
	v_add_u32_e32 v146, 0xffffee00, v146
	v_add_u32_e32 v144, 0xffffdc00, v144
	v_add_u32_e32 v142, 0xffffca00, v142
	v_mul_u32_u24_e32 v252, 0x60, v254
	v_add_u32_e32 v148, v148, v252
	v_add_u32_e32 v145, v145, v252
	v_add_u32_e32 v143, v143, v252
	v_add_u32_e32 v141, v141, v252
	v_add_u32_e32 v145, 0xffffffe0, v145
	v_add_u32_e32 v143, 0xffffffc0, v143
	v_add_u32_e32 v141, 0xffffffa0, v141
	v_lshrrev_b32_e32 v253, 6, v167
	s_nop 1
	v_readfirstlane_b32 s18, v253
	s_lshr_b32 s101, s18, 2
	s_or_b32 s19, s18, 4
	s_cmp_eq_u32 s19, 7
	s_cselect_b64 s[0:1], -1, 0
	s_cmp_eq_u32 s19, 6
	s_cselect_b64 s[16:17], -1, 0
	s_cmp_eq_u32 s19, 5
	s_cselect_b64 s[4:5], -1, 0
	s_cmp_eq_u32 s19, 4
	s_cselect_b64 s[8:9], -1, 0
	s_mov_b64 s[10:11], 0
	s_mov_b64 s[12:13], 0
	s_mov_b64 s[14:15], 0
	s_bfe_u32 s42, s2, 0x20003
	s_mov_b32 s98, 0
	s_cmp_eq_u32 s101, 0
	s_cselect_b32 s99, 0x14400, 0
	s_cselect_b32 s100, 0, 0x400
	v_add_u32_e32 v253, 0x14000, v147
	v_mov_b32_e32 v254, 1.0
	v_mov_b32_e32 v252, 0
	ds_write2_b32 v253, v254, v252 offset1:32
	s_waitcnt lgkmcnt(0)
	s_barrier
	s_cmp_eq_u32 s101, 0
	s_cbranch_scc1 .Lpp_f_nox
	s_barrier
.Lpp_f_nox:
.LBB0_292:
	s_cmp_eq_u32 s80, 0
	s_cselect_b32 s43, 0xff, s42
	s_add_u32 s18, s80, 0x7ff0000
	s_addc_u32 s19, s81, 0
	v_lshl_add_u64 v[252:253], v[136:137], 0, s[18:19]
	v_add_u32_e32 v32, s97, v139
	v_cmp_lt_i32_e64 s[18:19], -1, v32
	v_cmp_gt_i32_e64 s[20:21], s92, v32
	s_and_b64 s[18:19], s[18:19], s[20:21]
	v_add_u32_e32 v33, 9, v32
	s_waitcnt vmcnt(10)
	v_cndmask_b32_e64 v71, 0, v71, s[18:19]
	v_cndmask_b32_e64 v70, 0, v70, s[18:19]
	v_cndmask_b32_e64 v69, 0, v69, s[18:19]
	v_cndmask_b32_e64 v68, 0, v68, s[18:19]
	v_cmp_lt_i32_e64 s[18:19], -10, v32
	v_cmp_gt_i32_e64 s[20:21], s92, v33
	s_and_b64 s[18:19], s[18:19], s[20:21]
	v_add_u32_e32 v33, 10, v32
	s_waitcnt vmcnt(1)
	v_cndmask_b32_e64 v107, 0, v107, s[18:19]
	v_cndmask_b32_e64 v106, 0, v106, s[18:19]
	v_cndmask_b32_e64 v105, 0, v105, s[18:19]
	v_cndmask_b32_e64 v104, 0, v104, s[18:19]
	v_cmp_lt_i32_e64 s[18:19], -11, v32
	v_cmp_gt_i32_e64 s[20:21], s92, v33
	ds_read_b128 v[60:63], v150
	ds_read_b128 v[52:55], v150 offset:16
	ds_read_b128 v[44:47], v150 offset:528
	ds_read_b128 v[56:59], v150 offset:512
	ds_read_b128 v[40:43], v150 offset:1040
	ds_read_b128 v[48:51], v150 offset:1024
	ds_read_b128 v[120:123], v150 offset:2064
	ds_read_b128 v[124:127], v150 offset:2048
	ds_read_b128 v[32:35], v150 offset:1552
	ds_read_b128 v[36:39], v150 offset:1536
	v_lshlrev_b32_e32 v66, 16, v68
	v_and_b32_e32 v67, 0xffff0000, v68
	v_lshlrev_b32_e32 v154, 16, v69
	v_and_b32_e32 v155, 0xffff0000, v69
	v_lshlrev_b32_e32 v168, 16, v70
	v_and_b32_e32 v169, 0xffff0000, v70
	s_waitcnt lgkmcnt(2)
	v_pk_fma_f32 v[66:67], v[60:61], v[66:67], v[124:125]
	v_pk_fma_f32 v[154:155], v[62:63], v[154:155], v[126:127]
	v_pk_fma_f32 v[168:169], v[52:53], v[168:169], v[120:121]
	v_lshlrev_b32_e32 v170, 16, v71
	v_and_b32_e32 v171, 0xffff0000, v71
	v_lshlrev_b32_e32 v172, 16, v72
	v_and_b32_e32 v173, 0xffff0000, v72
	v_lshlrev_b32_e32 v174, 16, v73
	v_and_b32_e32 v175, 0xffff0000, v73
	v_lshlrev_b32_e32 v176, 16, v74
	v_and_b32_e32 v177, 0xffff0000, v74
	v_pk_fma_f32 v[170:171], v[54:55], v[170:171], v[122:123]
	v_pk_fma_f32 v[66:67], v[56:57], v[172:173], v[66:67]
	v_pk_fma_f32 v[154:155], v[58:59], v[174:175], v[154:155]
	v_pk_fma_f32 v[168:169], v[44:45], v[176:177], v[168:169]
	v_lshlrev_b32_e32 v178, 16, v75
	v_and_b32_e32 v179, 0xffff0000, v75
	v_lshlrev_b32_e32 v180, 16, v76
	v_and_b32_e32 v181, 0xffff0000, v76
	v_lshlrev_b32_e32 v182, 16, v77
	v_and_b32_e32 v183, 0xffff0000, v77
	v_lshlrev_b32_e32 v184, 16, v78
	v_and_b32_e32 v185, 0xffff0000, v78
	v_pk_fma_f32 v[170:171], v[46:47], v[178:179], v[170:171]
	v_pk_fma_f32 v[66:67], v[48:49], v[180:181], v[66:67]
	v_pk_fma_f32 v[154:155], v[50:51], v[182:183], v[154:155]
	v_pk_fma_f32 v[168:169], v[40:41], v[184:185], v[168:169]
	v_lshlrev_b32_e32 v186, 16, v79
	v_and_b32_e32 v187, 0xffff0000, v79
	v_lshlrev_b32_e32 v188, 16, v80
	v_and_b32_e32 v189, 0xffff0000, v80
	v_lshlrev_b32_e32 v190, 16, v81
	v_and_b32_e32 v191, 0xffff0000, v81
	v_lshlrev_b32_e32 v192, 16, v82
	v_and_b32_e32 v193, 0xffff0000, v82
	v_pk_fma_f32 v[170:171], v[42:43], v[186:187], v[170:171]
	s_waitcnt lgkmcnt(0)
; #define LAS __attribute__((address_space(3)))
; __device__ __forceinline__ unsigned cvt_pk_bf16(float lo, float hi) { unsigned r; asm volatile("v_cvt_pk_bf16_f32 %0, %1, %2" : "=v"(r) : "v"(lo), "v"(hi)); return r; }
; __device__ __forceinline__ float bf_lo(unsigned u) { return __uint_as_float(u << 16); }
; __device__ __forceinline__ float bf_hi(unsigned u) { return __uint_as_float(u & 0xffff0000u); }
; template <int dir>
; __device__ __forceinline__ void lru_pass(LAS unsigned char* lds, const Params& P, int b, int h, int q, bool dry) {
;     ...
;             for (int j = 0; j < 8; ++j) {
;                 f32x2 o0 = cb2[0], o1 = cb2[1], o2 = cb2[2], o3 = cb2[3];
; #pragma unroll
;                 for (int k = 0; k < 4; ++k) { const u32x4 rr = rows[j + k];
;                     o0 = cw2[k][0] * (f32x2){bf_lo(rr.x), bf_hi(rr.x)} + o0; o1 = cw2[k][1] * (f32x2){bf_lo(rr.y), bf_hi(rr.y)} + o1;
;                     o2 = cw2[k][2] * (f32x2){bf_lo(rr.z), bf_hi(rr.z)} + o2; o3 = cw2[k][3] * (f32x2){bf_lo(rr.w), bf_hi(rr.w)} + o3; }
;                 u32x4 w; w.x = cvt_pk_bf16(o0[0], o0[1]); w.y = cvt_pk_bf16(o1[0], o1[1]); w.z = cvt_pk_bf16(o2[0], o2[1]); w.w = cvt_pk_bf16(o3[0], o3[1]);
;                 *(LAS u32x4*)(XC + (tr * 8 + j) * XC_PITCH + cgp * 16) = w;
;             }
	v_pk_fma_f32 v[66:67], v[36:37], v[188:189], v[66:67]
	v_pk_fma_f32 v[154:155], v[38:39], v[190:191], v[154:155]
	v_pk_fma_f32 v[194:195], v[32:33], v[192:193], v[168:169]
	v_lshlrev_b32_e32 v196, 16, v83
	v_and_b32_e32 v197, 0xffff0000, v83
	v_cvt_pk_bf16_f32 v168, v66, v67
	v_cvt_pk_bf16_f32 v169, v154, v155
	v_pk_fma_f32 v[198:199], v[34:35], v[196:197], v[170:171]
	v_cvt_pk_bf16_f32 v170, v194, v195
	v_pk_fma_f32 v[66:67], v[60:61], v[172:173], v[124:125]
	v_cvt_pk_bf16_f32 v171, v198, v199
	ds_write_b128 v151, v[168:171]
	s_cmp_eq_u32 s43, 0
	s_cselect_b64 exec, -1, 0
	global_store_dwordx4 v[252:253], v[168:171], off offset:-1024 sc1
	s_mov_b64 exec, -1
	s_nop 0
	v_pk_fma_f32 v[154:155], v[62:63], v[174:175], v[126:127]
	v_pk_fma_f32 v[168:169], v[52:53], v[176:177], v[120:121]
	v_pk_fma_f32 v[170:171], v[54:55], v[178:179], v[122:123]
	v_pk_fma_f32 v[66:67], v[56:57], v[180:181], v[66:67]
	v_pk_fma_f32 v[154:155], v[58:59], v[182:183], v[154:155]
	v_pk_fma_f32 v[168:169], v[44:45], v[184:185], v[168:169]
	v_pk_fma_f32 v[170:171], v[46:47], v[186:187], v[170:171]
	v_pk_fma_f32 v[66:67], v[48:49], v[188:189], v[66:67]
	v_pk_fma_f32 v[154:155], v[50:51], v[190:191], v[154:155]
	v_pk_fma_f32 v[168:169], v[40:41], v[192:193], v[168:169]
	v_lshlrev_b32_e32 v172, 16, v84
	v_and_b32_e32 v173, 0xffff0000, v84
	v_lshlrev_b32_e32 v174, 16, v85
	v_and_b32_e32 v175, 0xffff0000, v85
	v_lshlrev_b32_e32 v176, 16, v86
	v_and_b32_e32 v177, 0xffff0000, v86
	v_pk_fma_f32 v[170:171], v[42:43], v[196:197], v[170:171]
	v_pk_fma_f32 v[66:67], v[36:37], v[172:173], v[66:67]
	v_pk_fma_f32 v[154:155], v[38:39], v[174:175], v[154:155]
	v_pk_fma_f32 v[178:179], v[32:33], v[176:177], v[168:169]
	v_lshlrev_b32_e32 v194, 16, v87
	v_and_b32_e32 v195, 0xffff0000, v87
	v_cvt_pk_bf16_f32 v168, v66, v67
	v_cvt_pk_bf16_f32 v169, v154, v155
	v_pk_fma_f32 v[198:199], v[34:35], v[194:195], v[170:171]
	v_cvt_pk_bf16_f32 v170, v178, v179
	v_pk_fma_f32 v[66:67], v[60:61], v[180:181], v[124:125]
	v_cvt_pk_bf16_f32 v171, v198, v199
	ds_write_b128 v151, v[168:171] offset:272
	s_cmp_eq_u32 s43, 0
	s_cselect_b64 exec, -1, 0
	global_store_dwordx4 v[252:253], v[168:171], off offset:-768 sc1
	s_mov_b64 exec, -1
	s_nop 0
	v_pk_fma_f32 v[154:155], v[62:63], v[182:183], v[126:127]
	v_pk_fma_f32 v[168:169], v[52:53], v[184:185], v[120:121]
	v_pk_fma_f32 v[170:171], v[54:55], v[186:187], v[122:123]
	v_pk_fma_f32 v[66:67], v[56:57], v[188:189], v[66:67]
	v_pk_fma_f32 v[154:155], v[58:59], v[190:191], v[154:155]
	v_pk_fma_f32 v[168:169], v[44:45], v[192:193], v[168:169]
	v_pk_fma_f32 v[170:171], v[46:47], v[196:197], v[170:171]
	v_pk_fma_f32 v[66:67], v[48:49], v[172:173], v[66:67]
	v_pk_fma_f32 v[154:155], v[50:51], v[174:175], v[154:155]
	v_pk_fma_f32 v[168:169], v[40:41], v[176:177], v[168:169]
	v_lshlrev_b32_e32 v178, 16, v88
	v_and_b32_e32 v179, 0xffff0000, v88
	v_lshlrev_b32_e32 v180, 16, v89
	v_and_b32_e32 v181, 0xffff0000, v89
	v_lshlrev_b32_e32 v182, 16, v90
	v_and_b32_e32 v183, 0xffff0000, v90
	v_pk_fma_f32 v[170:171], v[42:43], v[194:195], v[170:171]
	v_pk_fma_f32 v[66:67], v[36:37], v[178:179], v[66:67]
	v_pk_fma_f32 v[154:155], v[38:39], v[180:181], v[154:155]
	v_pk_fma_f32 v[184:185], v[32:33], v[182:183], v[168:169]
	v_lshlrev_b32_e32 v186, 16, v91
	v_and_b32_e32 v187, 0xffff0000, v91
	v_cvt_pk_bf16_f32 v168, v66, v67
	v_cvt_pk_bf16_f32 v169, v154, v155
	v_pk_fma_f32 v[198:199], v[34:35], v[186:187], v[170:171]
	v_cvt_pk_bf16_f32 v170, v184, v185
	v_pk_fma_f32 v[66:67], v[60:61], v[188:189], v[124:125]
	v_cvt_pk_bf16_f32 v171, v198, v199
	ds_write_b128 v151, v[168:171] offset:544
	s_cmp_eq_u32 s43, 1
	s_cselect_b64 exec, -1, 0
	global_store_dwordx4 v[252:253], v[168:171], off offset:-512 sc1
	s_mov_b64 exec, -1
	s_nop 0
	v_pk_fma_f32 v[154:155], v[62:63], v[190:191], v[126:127]
	v_pk_fma_f32 v[168:169], v[52:53], v[192:193], v[120:121]
	v_pk_fma_f32 v[170:171], v[54:55], v[196:197], v[122:123]
	v_pk_fma_f32 v[66:67], v[56:57], v[172:173], v[66:67]
	v_pk_fma_f32 v[154:155], v[58:59], v[174:175], v[154:155]
	v_pk_fma_f32 v[168:169], v[44:45], v[176:177], v[168:169]
	v_pk_fma_f32 v[170:171], v[46:47], v[194:195], v[170:171]
	v_pk_fma_f32 v[66:67], v[48:49], v[178:179], v[66:67]
	v_pk_fma_f32 v[154:155], v[50:51], v[180:181], v[154:155]
	v_pk_fma_f32 v[168:169], v[40:41], v[182:183], v[168:169]
	v_lshlrev_b32_e32 v184, 16, v92
	v_and_b32_e32 v185, 0xffff0000, v92
	v_lshlrev_b32_e32 v188, 16, v93
	v_and_b32_e32 v189, 0xffff0000, v93
	v_lshlrev_b32_e32 v190, 16, v94
	v_and_b32_e32 v191, 0xffff0000, v94
	v_pk_fma_f32 v[170:171], v[42:43], v[186:187], v[170:171]
	v_pk_fma_f32 v[66:67], v[36:37], v[184:185], v[66:67]
	v_pk_fma_f32 v[154:155], v[38:39], v[188:189], v[154:155]
	v_pk_fma_f32 v[192:193], v[32:33], v[190:191], v[168:169]
	v_lshlrev_b32_e32 v196, 16, v95
	v_and_b32_e32 v197, 0xffff0000, v95
	v_cvt_pk_bf16_f32 v168, v66, v67
	v_cvt_pk_bf16_f32 v169, v154, v155
	v_pk_fma_f32 v[198:199], v[34:35], v[196:197], v[170:171]
	v_cvt_pk_bf16_f32 v170, v192, v193
	v_pk_fma_f32 v[66:67], v[60:61], v[172:173], v[124:125]
	v_cvt_pk_bf16_f32 v171, v198, v199
	ds_write_b128 v151, v[168:171] offset:816
	s_cmp_eq_u32 s43, 1
	s_cselect_b64 exec, -1, 0
	global_store_dwordx4 v[252:253], v[168:171], off offset:-256 sc1
	s_mov_b64 exec, -1
	s_nop 0
	v_pk_fma_f32 v[154:155], v[62:63], v[174:175], v[126:127]
	v_pk_fma_f32 v[168:169], v[52:53], v[176:177], v[120:121]
	v_pk_fma_f32 v[170:171], v[54:55], v[194:195], v[122:123]
	v_pk_fma_f32 v[66:67], v[56:57], v[178:179], v[66:67]
	v_pk_fma_f32 v[154:155], v[58:59], v[180:181], v[154:155]
	v_pk_fma_f32 v[168:169], v[44:45], v[182:183], v[168:169]
; #define LAS __attribute__((address_space(3)))
; __device__ __forceinline__ unsigned cvt_pk_bf16(float lo, float hi) { unsigned r; asm volatile("v_cvt_pk_bf16_f32 %0, %1, %2" : "=v"(r) : "v"(lo), "v"(hi)); return r; }
; __device__ __forceinline__ float bf_lo(unsigned u) { return __uint_as_float(u << 16); }
; __device__ __forceinline__ float bf_hi(unsigned u) { return __uint_as_float(u & 0xffff0000u); }
; template <int dir>
; __device__ __forceinline__ void lru_pass(LAS unsigned char* lds, const Params& P, int b, int h, int q, bool dry) {
;     ...
;             for (int j = 0; j < 8; ++j) {
;                 f32x2 o0 = cb2[0], o1 = cb2[1], o2 = cb2[2], o3 = cb2[3];
; #pragma unroll
;                 for (int k = 0; k < 4; ++k) { const u32x4 rr = rows[j + k];
;                     o0 = cw2[k][0] * (f32x2){bf_lo(rr.x), bf_hi(rr.x)} + o0; o1 = cw2[k][1] * (f32x2){bf_lo(rr.y), bf_hi(rr.y)} + o1;
;                     o2 = cw2[k][2] * (f32x2){bf_lo(rr.z), bf_hi(rr.z)} + o2; o3 = cw2[k][3] * (f32x2){bf_lo(rr.w), bf_hi(rr.w)} + o3; }
;                 u32x4 w; w.x = cvt_pk_bf16(o0[0], o0[1]); w.y = cvt_pk_bf16(o1[0], o1[1]); w.z = cvt_pk_bf16(o2[0], o2[1]); w.w = cvt_pk_bf16(o3[0], o3[1]);
;                 *(LAS u32x4*)(XC + (tr * 8 + j) * XC_PITCH + cgp * 16) = w;
;             }
; #pragma unroll
;             for (int i = 0; i < NIN; ++i) { const int id = tid + i * NTHREADS;
;                 if (dir == 0) *(LAS u32x4*)(TIN + (id >> 2) * IO_NP + (id & 3) * 16) = inr[i];
;                 else *(LAS u32x4*)(TIN + (id >> 3) * IO_WP + (id & 7) * 16) = inr[i]; }
;             LruTile nxt = cur;
;             if (sc < 8) { nxt = lru_tile(Z, ZC, b, h, dir, sc + 1); lru_load_rows(rows, nxt, tr, cgp);
; #pragma unroll
;                 for (int i = 0; i < NIN; ++i) { const int id = tid + i * NTHREADS;
;                     if (dir == 0) inr[i] = *(const u32x4*)(Zg + (size_t)(nxt.t0 + (id >> 2)) * 128 + (id & 3) * 8);
;                     else inr[i] = *(const u32x4*)(Hg + (size_t)(nxt.t0 + (id >> 3)) * DM + (id & 7) * 4); } }
	v_pk_fma_f32 v[170:171], v[46:47], v[186:187], v[170:171]
	v_pk_fma_f32 v[66:67], v[48:49], v[184:185], v[66:67]
	v_pk_fma_f32 v[154:155], v[50:51], v[188:189], v[154:155]
	v_pk_fma_f32 v[168:169], v[40:41], v[190:191], v[168:169]
	v_lshlrev_b32_e32 v172, 16, v96
	v_and_b32_e32 v173, 0xffff0000, v96
	v_lshlrev_b32_e32 v174, 16, v97
	v_and_b32_e32 v175, 0xffff0000, v97
	v_lshlrev_b32_e32 v176, 16, v98
	v_and_b32_e32 v177, 0xffff0000, v98
	v_pk_fma_f32 v[170:171], v[42:43], v[196:197], v[170:171]
	v_pk_fma_f32 v[66:67], v[36:37], v[172:173], v[66:67]
	v_pk_fma_f32 v[154:155], v[38:39], v[174:175], v[154:155]
	v_pk_fma_f32 v[192:193], v[32:33], v[176:177], v[168:169]
	v_lshlrev_b32_e32 v194, 16, v99
	v_and_b32_e32 v195, 0xffff0000, v99
	v_cvt_pk_bf16_f32 v168, v66, v67
	v_cvt_pk_bf16_f32 v169, v154, v155
	v_pk_fma_f32 v[198:199], v[34:35], v[194:195], v[170:171]
	v_cvt_pk_bf16_f32 v170, v192, v193
	v_pk_fma_f32 v[66:67], v[60:61], v[178:179], v[124:125]
	v_cvt_pk_bf16_f32 v171, v198, v199
	ds_write_b128 v151, v[168:171] offset:1088
	s_cmp_eq_u32 s43, 2
	s_cselect_b64 exec, -1, 0
	global_store_dwordx4 v[252:253], v[168:171], off sc1
	s_mov_b64 exec, -1
	s_nop 0
	v_pk_fma_f32 v[154:155], v[62:63], v[180:181], v[126:127]
	v_pk_fma_f32 v[168:169], v[52:53], v[182:183], v[120:121]
	v_pk_fma_f32 v[170:171], v[54:55], v[186:187], v[122:123]
	v_pk_fma_f32 v[66:67], v[56:57], v[184:185], v[66:67]
	v_pk_fma_f32 v[154:155], v[58:59], v[188:189], v[154:155]
	v_pk_fma_f32 v[168:169], v[44:45], v[190:191], v[168:169]
	v_pk_fma_f32 v[170:171], v[46:47], v[196:197], v[170:171]
	v_pk_fma_f32 v[66:67], v[48:49], v[172:173], v[66:67]
	v_pk_fma_f32 v[154:155], v[50:51], v[174:175], v[154:155]
	v_pk_fma_f32 v[168:169], v[40:41], v[176:177], v[168:169]
	v_lshlrev_b32_e32 v178, 16, v100
	v_and_b32_e32 v179, 0xffff0000, v100
	v_lshlrev_b32_e32 v180, 16, v101
	v_and_b32_e32 v181, 0xffff0000, v101
	v_lshlrev_b32_e32 v182, 16, v102
	v_and_b32_e32 v183, 0xffff0000, v102
	v_pk_fma_f32 v[170:171], v[42:43], v[194:195], v[170:171]
	v_pk_fma_f32 v[66:67], v[36:37], v[178:179], v[66:67]
	v_pk_fma_f32 v[154:155], v[38:39], v[180:181], v[154:155]
	v_pk_fma_f32 v[186:187], v[32:33], v[182:183], v[168:169]
	v_lshlrev_b32_e32 v192, 16, v103
	v_and_b32_e32 v193, 0xffff0000, v103
	v_cvt_pk_bf16_f32 v168, v66, v67
	v_cvt_pk_bf16_f32 v169, v154, v155
	s_and_b64 s[18:19], s[18:19], s[20:21]
	v_pk_fma_f32 v[198:199], v[34:35], v[192:193], v[170:171]
	v_cvt_pk_bf16_f32 v170, v186, v187
	v_pk_fma_f32 v[66:67], v[60:61], v[184:185], v[124:125]
	v_cvt_pk_bf16_f32 v171, v198, v199
	ds_write_b128 v151, v[168:171] offset:1360
	s_cmp_eq_u32 s43, 2
	s_cselect_b64 exec, -1, 0
	global_store_dwordx4 v[252:253], v[168:171], off offset:256 sc1
	s_mov_b64 exec, -1
	s_nop 0
	v_pk_fma_f32 v[168:169], v[52:53], v[190:191], v[120:121]
	v_pk_fma_f32 v[60:61], v[60:61], v[172:173], v[124:125]
	v_pk_fma_f32 v[52:53], v[52:53], v[176:177], v[120:121]
	s_waitcnt vmcnt(0)
	v_cndmask_b32_e64 v108, 0, v108, s[18:19]
	v_pk_fma_f32 v[154:155], v[62:63], v[188:189], v[126:127]
	v_pk_fma_f32 v[66:67], v[56:57], v[172:173], v[66:67]
	v_pk_fma_f32 v[168:169], v[44:45], v[176:177], v[168:169]
	v_lshlrev_b32_e32 v184, 16, v104
	v_and_b32_e32 v185, 0xffff0000, v104
	v_lshlrev_b32_e32 v188, 16, v106
	v_and_b32_e32 v189, 0xffff0000, v106
	v_pk_fma_f32 v[62:63], v[62:63], v[174:175], v[126:127]
	v_pk_fma_f32 v[56:57], v[56:57], v[178:179], v[60:61]
	v_pk_fma_f32 v[44:45], v[44:45], v[182:183], v[52:53]
	v_cndmask_b32_e64 v109, 0, v109, s[18:19]
	v_pk_fma_f32 v[154:155], v[58:59], v[174:175], v[154:155]
	v_pk_fma_f32 v[66:67], v[48:49], v[178:179], v[66:67]
	v_pk_fma_f32 v[168:169], v[40:41], v[182:183], v[168:169]
	v_lshlrev_b32_e32 v186, 16, v105
	v_and_b32_e32 v187, 0xffff0000, v105
	v_pk_fma_f32 v[58:59], v[58:59], v[180:181], v[62:63]
	v_pk_fma_f32 v[48:49], v[48:49], v[184:185], v[56:57]
	v_pk_fma_f32 v[40:41], v[40:41], v[188:189], v[44:45]
	v_lshlrev_b32_e32 v44, 16, v108
	v_and_b32_e32 v45, 0xffff0000, v108
	v_cndmask_b32_e64 v110, 0, v110, s[18:19]
	v_pk_fma_f32 v[170:171], v[54:55], v[196:197], v[122:123]
	v_pk_fma_f32 v[154:155], v[50:51], v[180:181], v[154:155]
	v_pk_fma_f32 v[66:67], v[36:37], v[184:185], v[66:67]
	v_pk_fma_f32 v[54:55], v[54:55], v[194:195], v[122:123]
	v_pk_fma_f32 v[50:51], v[50:51], v[186:187], v[58:59]
	v_pk_fma_f32 v[36:37], v[36:37], v[44:45], v[48:49]
	v_lshlrev_b32_e32 v44, 16, v109
	v_and_b32_e32 v45, 0xffff0000, v109
	v_cndmask_b32_e64 v111, 0, v111, s[18:19]
	v_pk_fma_f32 v[170:171], v[46:47], v[194:195], v[170:171]
	v_pk_fma_f32 v[154:155], v[38:39], v[186:187], v[154:155]
	v_lshlrev_b32_e32 v196, 16, v107
	v_and_b32_e32 v197, 0xffff0000, v107
	v_pk_fma_f32 v[46:47], v[46:47], v[192:193], v[54:55]
	v_pk_fma_f32 v[38:39], v[38:39], v[44:45], v[50:51]
	v_lshlrev_b32_e32 v44, 16, v110
	v_and_b32_e32 v45, 0xffff0000, v110
	v_pk_fma_f32 v[170:171], v[42:43], v[192:193], v[170:171]
	v_pk_fma_f32 v[190:191], v[32:33], v[188:189], v[168:169]
	v_pk_fma_f32 v[42:43], v[42:43], v[196:197], v[46:47]
	v_pk_fma_f32 v[40:41], v[32:33], v[44:45], v[40:41]
	v_lshlrev_b32_e32 v32, 16, v111
	v_and_b32_e32 v33, 0xffff0000, v111
	v_pk_fma_f32 v[198:199], v[34:35], v[196:197], v[170:171]
	v_cvt_pk_bf16_f32 v168, v66, v67
	v_cvt_pk_bf16_f32 v169, v154, v155
	v_cvt_pk_bf16_f32 v170, v190, v191
	v_pk_fma_f32 v[42:43], v[34:35], v[32:33], v[42:43]
	v_cvt_pk_bf16_f32 v171, v198, v199
	ds_write_b128 v151, v[168:171] offset:1632
	s_cmp_eq_u32 s43, 3
	s_cselect_b64 exec, -1, 0
	global_store_dwordx4 v[252:253], v[168:171], off offset:512 sc1
	s_mov_b64 exec, -1
	s_nop 0
	v_cvt_pk_bf16_f32 v32, v36, v37
	v_cvt_pk_bf16_f32 v33, v38, v39
	v_cvt_pk_bf16_f32 v34, v40, v41
	v_cvt_pk_bf16_f32 v35, v42, v43
	s_cmp_eq_u32 s43, 3
	s_cselect_b64 exec, -1, 0
	global_store_dwordx4 v[252:253], v[32:35], off offset:768 sc1
	s_mov_b64 exec, -1
	s_nop 0
	s_cmp_eq_u32 s80, 0x80000
	ds_write_b128 v151, v[32:35] offset:1904
	ds_write_b128 v158, v[112:115]
	ds_write_b128 v159, v[116:119]
	s_cbranch_scc1 .LBB0_294
	v_lshl_add_u64 v[32:33], v[136:137], 0, s[80:81]
	global_load_dwordx4 v[68:71], v[32:33], off offset:-1280
	global_load_dwordx4 v[72:75], v[32:33], off offset:-1024
	global_load_dwordx4 v[76:79], v[32:33], off offset:-768
	global_load_dwordx4 v[80:83], v[32:33], off offset:-512
	global_load_dwordx4 v[84:87], v[32:33], off offset:-256
	global_load_dwordx4 v[88:91], v[32:33], off
	global_load_dwordx4 v[92:95], v[32:33], off offset:256
	global_load_dwordx4 v[96:99], v[32:33], off offset:512
	global_load_dwordx4 v[100:103], v[32:33], off offset:768
	global_load_dwordx4 v[104:107], v[32:33], off offset:1024
	v_lshl_add_u64 v[34:35], v[134:135], 0, s[80:81]
	global_load_dwordx4 v[108:111], v[32:33], off offset:1280
	global_load_dwordx4 v[112:115], v[34:35], off
	v_lshl_add_u64 v[32:33], v[132:133], 0, s[80:81]
	global_load_dwordx4 v[116:119], v[32:33], off
	s_movk_i32 s92, 0x800
	s_mov_b32 s20, s90
	s_branch .LBB0_295

; #define LAS __attribute__((address_space(3)))
; #define LDS_BARRIER() do { asm volatile("s_waitcnt lgkmcnt(0)" ::: "memory"); __builtin_amdgcn_s_barrier(); asm volatile("" ::: "memory"); } while (0)
; template <int dir>
; __device__ __forceinline__ void lru_pass(LAS unsigned char* lds, const Params& P, int b, int h, int q, bool dry) {
;     ...
;         LDS_BARRIER();
;         if (dir == 0) {
; #pragma unroll
;             for (int i = 0; i < 4; ++i) { const int id = tid + i * NTHREADS; *(u32x4*)(Hg + (size_t)(t0_prev + (id >> 3)) * DM + (id & 7) * 4) = *(const LAS u32x4*)(TOUT + (id >> 3) * IO_WP + (id & 7) * 16); }
; __device__ __forceinline__ void lru_strip(LAS unsigned char* lds, const Params& P, int strip, bool dry) {
;     ...
;     lru_pass<0>(lds, P, b, h, q, dry);
;     asm volatile("s_waitcnt vmcnt(0)" ::: "memory"); __syncthreads();
;     if (tid < 64) { __builtin_amdgcn_fence(__ATOMIC_ACQUIRE, "agent"); asm volatile("s_waitcnt vmcnt(0)" ::: "memory"); }
;     __syncthreads();
;     lru_pass<1>(lds, P, b, h, q, dry);
.Lpp_f_noy:
	s_waitcnt lgkmcnt(0)
	s_barrier
	v_add_u32_e32 v0, v129, v149
	ds_read_b128 v[0:3], v0
	v_add_u32_e32 v4, s97, v148
	v_ashrrev_i32_e32 v5, 31, v4
	v_lshlrev_b64 v[4:5], 12, v[4:5]
	v_lshl_add_u64 v[8:9], v[130:131], 0, v[4:5]
	v_add_u32_e32 v4, v129, v146
	ds_read_b128 v[4:7], v4
	s_waitcnt lgkmcnt(1)
	global_store_dwordx4 v[8:9], v[0:3], off
	v_cmp_gt_i32_e32 vcc, 64, v128
	s_nop 0
	v_add_u32_e32 v0, s97, v145
	v_ashrrev_i32_e32 v1, 31, v0
	v_lshlrev_b64 v[0:1], 12, v[0:1]
	v_lshl_add_u64 v[0:1], v[130:131], 0, v[0:1]
	s_waitcnt lgkmcnt(0)
	global_store_dwordx4 v[0:1], v[4:7], off
	v_add_u32_e32 v0, v129, v144
	ds_read_b128 v[0:3], v0
	v_add_u32_e32 v4, s97, v143
	v_ashrrev_i32_e32 v5, 31, v4
	v_lshlrev_b64 v[4:5], 12, v[4:5]
	v_lshl_add_u64 v[8:9], v[130:131], 0, v[4:5]
	v_add_u32_e32 v4, v129, v142
	ds_read_b128 v[4:7], v4
	s_waitcnt lgkmcnt(1)
	global_store_dwordx4 v[8:9], v[0:3], off
	s_nop 1
	v_add_u32_e32 v0, s97, v141
	v_ashrrev_i32_e32 v1, 31, v0
	v_lshlrev_b64 v[0:1], 12, v[0:1]
	v_lshl_add_u64 v[0:1], v[130:131], 0, v[0:1]
	s_waitcnt lgkmcnt(0)
	global_store_dwordx4 v[0:1], v[4:7], off
	s_waitcnt vmcnt(0) lgkmcnt(0)
	s_barrier
	s_lshr_b32 s18, s2, 5
	s_lshl_b32 s18, s18, 3
	s_and_b32 s19, s2, 7
	s_or_b32 s18, s18, s19
	s_lshl_b32 s18, s18, 8
	s_add_u32 s18, s18, 0x84008
	s_add_u32 s18, s22, s18
	s_addc_u32 s19, s23, 0
	v_mov_b32_e32 v0, 0
	v_mov_b32_e32 v1, 1
	v_cmp_eq_u32_e32 vcc, 0, v167
	s_and_saveexec_b64 s[20:21], vcc
	global_atomic_add v0, v1, s[18:19]
	s_or_b64 exec, exec, s[20:21]
	s_add_u32 s42, s22, 0x1b00000
	s_addc_u32 s43, s23, 0
	v_mov_b32_e32 v32, v167
	s_or_b32 s0, s26, 16
	v_and_b32_e32 v15, 31, v32
	v_or_b32_e32 v17, s28, v15
	v_add_u32_e32 v13, 0x200, v32
	v_or_b32_e32 v8, s27, v17
	v_ashrrev_i32_e32 v11, 9, v32
	v_ashrrev_i32_e32 v14, 9, v13
	v_lshlrev_b32_e32 v8, 2, v8
	v_mov_b32_e32 v9, v65
	v_lshl_add_u32 v2, v11, 3, s0
	v_lshl_add_u32 v6, v14, 3, s0
	v_lshl_add_u64 v[8:9], s[64:65], 0, v[8:9]
	s_movk_i32 s0, 0x1000
	v_add_co_u32_e32 v8, vcc, s0, v8
	v_and_b32_e32 v12, 15, v32
	s_nop 0
	v_addc_co_u32_e32 v9, vcc, 0, v9, vcc
	global_load_dword v16, v[8:9], off
	v_bfe_u32 v10, v32, 4, 5
	v_lshlrev_b32_e32 v64, 4, v12
	v_ashrrev_i32_e32 v3, 31, v2
	v_ashrrev_i32_e32 v7, 31, v6
	v_or_b32_e32 v4, s28, v10
	v_lshl_add_u64 v[0:1], s[38:39], 0, v[64:65]
	v_lshlrev_b64 v[2:3], 15, v[2:3]
	v_lshlrev_b64 v[6:7], 15, v[6:7]
	v_lshlrev_b32_e32 v4, 8, v4
	v_mov_b32_e32 v5, v65
	v_lshl_add_u64 v[2:3], v[0:1], 0, v[2:3]
	v_lshl_add_u64 v[0:1], v[0:1], 0, v[6:7]
	v_lshl_add_u64 v[2:3], v[2:3], 0, v[4:5]
	v_lshl_add_u64 v[4:5], v[0:1], 0, v[4:5]
	global_load_dwordx4 v[0:3], v[2:3], off
	s_nop 0
	global_load_dwordx4 v[4:7], v[4:5], off
	v_lshrrev_b32_e32 v8, 1, v32
	v_lshlrev_b32_e32 v9, 2, v32
	v_and_b32_e32 v20, 12, v8
	v_lshl_or_b32 v11, v11, 5, v10
	v_add_u32_e32 v8, s88, v64
	v_lshl_or_b32 v14, v14, 5, v10
	v_mad_u64_u32 v[10:11], s[6:7], v11, s89, v[8:9]
	s_or_b32 s8, s26, 8
	v_and_or_b32 v20, v9, 16, v20
	v_lshlrev_b32_e32 v21, 2, v17
	v_mad_u64_u32 v[8:9], s[6:7], v14, s89, v[8:9]
	v_lshl_or_b32 v9, s8, 9, v21
	global_load_dword v14, v9, s[58:59]
	s_nop 0
	global_load_dword v9, v9, s[62:63]
	s_mov_b32 s80, 0x3f2aaaab
	s_mov_b32 s81, 0x3f317218
	s_mov_b32 s91, 0x7f800000
	s_mov_b32 s92, 0x33800000
	v_ashrrev_i32_e32 v33, 4, v32
	v_lshlrev_b32_e32 v34, 3, v12
	v_readfirstlane_b32 s4, v32
	s_lshl_b64 s[0:1], s[78:79], 11
	s_lshl_b32 s5, s8, 14
	s_ashr_i32 s6, s4, 6
	s_add_u32 s26, s0, s5
	s_addc_u32 s27, s1, 0
	s_lshl_b32 s0, s28, 1
	v_readlane_b32 s1, v255, 10
	v_and_b32_e32 v19, 3, v32
	s_add_u32 s0, s1, s0
	v_bfe_u32 v18, v32, 5, 1
	v_add_u32_e32 v44, 0, v64
	v_lshlrev_b32_e32 v64, 4, v19
	s_addc_u32 s1, s3, 0
	v_lshl_add_u64 v[136:137], s[0:1], 0, v[64:65]
	s_lshl_b32 s0, s6, 5
	v_lshlrev_b32_e32 v46, 4, v18
	v_or_b32_e32 v37, s0, v46
	v_add_u32_e32 v158, s86, v64
	v_or_b32_e32 v64, 4, v37
	s_movk_i32 s93, 0x880
	v_ashrrev_i32_e32 v36, 3, v32
	v_ashrrev_i32_e32 v38, 3, v13
	v_ashrrev_i32_e32 v140, 2, v32
	v_sub_u32_e32 v39, 0xff, v37
	v_sub_u32_e32 v64, 0xff, v64
	v_lshl_add_u32 v160, v33, 3, -1
	v_mul_lo_u32 v52, v33, s93
	v_lshl_or_b32 v110, v33, 13, v34
	v_mov_b32_e32 v111, v65
	v_lshlrev_b64 v[110:111], 1, v[110:111]
	v_lshl_add_u64 v[108:109], s[48:49], 0, v[110:111]
	global_load_dwordx4 v[68:71], v[108:109], off offset:-2048
	global_load_dwordx4 v[72:75], v[108:109], off
	global_load_dwordx4 v[76:79], v[108:109], off offset:2048
	v_lshl_add_u64 v[108:109], s[50:51], 0, v[110:111]
	global_load_dwordx4 v[80:83], v[108:109], off
	v_lshl_add_u64 v[108:109], s[56:57], 0, v[110:111]
	global_load_dwordx4 v[84:87], v[108:109], off
	v_lshl_add_u64 v[108:109], s[60:61], 0, v[110:111]
	global_load_dwordx4 v[88:91], v[108:109], off
	v_lshl_add_u64 v[108:109], s[66:67], 0, v[110:111]
	global_load_dwordx4 v[92:95], v[108:109], off
	v_lshl_add_u64 v[108:109], s[70:71], 0, v[110:111]
	global_load_dwordx4 v[96:99], v[108:109], off
	v_lshl_add_u64 v[108:109], s[72:73], 0, v[110:111]
	global_load_dwordx4 v[100:103], v[108:109], off
	v_lshl_add_u64 v[108:109], s[74:75], 0, v[110:111]
	global_load_dwordx4 v[104:107], v[108:109], off
	v_lshl_add_u64 v[108:109], s[76:77], 0, v[110:111]
	global_load_dwordx4 v[108:111], v[108:109], off
	s_waitcnt vmcnt(14)
	ds_write_b128 v10, v[0:3]
	s_waitcnt vmcnt(13)
; #define LAS __attribute__((address_space(3)))
; template <int dir>
; __device__ __forceinline__ void lru_pass(LAS unsigned char* lds, const Params& P, int b, int h, int q, bool dry) {
;     ...
;             *(LAS u32x4*)(WB + (gate * 32 + n) * XC_PITCH + kc * 16) = *(const u32x4*)(LruW + ((size_t)((dir * 2 + gate) * 8 + h) * 128 + q * 32 + n) * 128 + kc * 8); }
;         const float br = -LOG2E * P.lru_ba[(dir * 8 + h) * 128 + chl], bi = -LOG2E * P.lru_bx[(dir * 8 + h) * 128 + chl];
;         const float lam = P.lru_lambda[dir * 1024 + ch];
;         const float cl = -8.0f * LOG2E * log1pf(__expf(-lam));
;     ...
;             { const int sl = 32 * wid + s_i; const int tlA = dir == 0 ? sl : 255 - sl;
;               const LAS unsigned char* ap = XC + tlA * XC_PITCH + 16 * g;
;               const LAS unsigned char* wrp = WB + nl * XC_PITCH + 16 * g; const LAS unsigned char* wip = wrp + 32 * XC_PITCH;
; #pragma unroll
;               for (int ks = 0; ks < 8; ++ks) { const bf16x8 A = *(const LAS bf16x8*)(ap + 32 * ks);
;                   const bf16x8 Br = *(const LAS bf16x8*)(wrp + 32 * ks), Bi = *(const LAS bf16x8*)(wip + 32 * ks);
;                   zr = __builtin_amdgcn_mfma_f32_32x32x16_bf16(A, Br, zr, 0, 0, 0); zi = __builtin_amdgcn_mfma_f32_32x32x16_bf16(A, Bi, zi, 0, 0, 0); } }
;             unsigned xcb[16], pk[16];
; #pragma unroll
;             for (int v = 0; v < 16; ++v) { const int s = sbase + v; const int tl = dir == 0 ? s : 255 - s; xcb[v] = *(const LAS bf16_t*)(XC + tl * XC_PITCH + chl * 2);
;                 if (dir == 0) pk[v] = *(const LAS bf16_t*)(TIN + tl * IO_NP + nl * 2); else pk[v] = *(const LAS unsigned*)(TIN + tl * IO_WP + nl * 4); }
;             float Pp = 1.f, E = 0.f;
; #pragma unroll
;             for (int v = 0; v < 16; ++v) {
;                 const float xcv = __uint_as_float(xcb[v] << 16);
;                 const float r = __builtin_amdgcn_rcpf(1.0f + __builtin_amdgcn_exp2f(zr[v]));
;                 const float ig = __builtin_amdgcn_rcpf(1.0f + __builtin_amdgcn_exp2f(zi[v]));
;                 const float a = __builtin_amdgcn_exp2f(cl * r);
;                 const float sq = __builtin_amdgcn_sqrtf(fmaf(-a, a, 1.0f));
;                 const float u = sq * ig * xcv;
;                 E = fmaf(a, E, u); Pp *= a; zr[v] = E; zi[v] = Pp; }
;             const float Po = __shfl_xor(Pp, 32), Eo = __shfl_xor(E, 32);
	ds_write_b128 v8, v[4:7]
	v_mul_f32_e32 v11, 0xbfb8aa3b, v16
	v_exp_f32_e32 v11, v11
	v_mul_lo_u32 v57, v39, s89
	v_mul_lo_u32 v58, v39, s30
	v_mul_lo_u32 v114, v64, s89
	v_add_f32_e32 v2, 1.0, v11
	v_add_f32_e32 v3, -1.0, v2
	v_frexp_mant_f32_e32 v4, v2
	v_cvt_f64_f32_e32 v[0:1], v2
	v_sub_f32_e32 v5, v3, v2
	v_frexp_exp_i32_f64_e32 v0, v[0:1]
	v_cmp_gt_f32_e32 vcc, s80, v4
	v_sub_f32_e32 v3, v11, v3
	v_add_f32_e32 v1, 1.0, v5
	v_subbrev_co_u32_e32 v0, vcc, 0, v0, vcc
	v_add_f32_e32 v1, v3, v1
	v_sub_u32_e32 v3, 0, v0
	v_ldexp_f32 v2, v2, v3
	v_ldexp_f32 v1, v1, v3
	v_add_f32_e32 v3, -1.0, v2
	v_add_f32_e32 v4, 1.0, v2
	v_add_f32_e32 v5, 1.0, v3
	v_add_f32_e32 v6, -1.0, v4
	v_sub_f32_e32 v5, v2, v5
	v_sub_f32_e32 v2, v2, v6
	v_add_f32_e32 v5, v1, v5
	v_add_f32_e32 v1, v1, v2
	v_add_f32_e32 v7, v4, v1
	v_rcp_f32_e32 v8, v7
	v_add_f32_e32 v2, v3, v5
	v_sub_f32_e32 v4, v7, v4
	v_sub_f32_e32 v3, v2, v3
	v_sub_f32_e32 v1, v1, v4
	v_mul_f32_e32 v4, v2, v8
	v_sub_f32_e32 v3, v5, v3
	v_mul_f32_e32 v5, v7, v4
	v_fma_f32 v10, v4, v7, -v5
	v_fmac_f32_e32 v10, v4, v1
	v_add_f32_e32 v16, v5, v10
	v_sub_f32_e32 v21, v2, v16
	v_sub_f32_e32 v2, v2, v21
	v_sub_f32_e32 v5, v16, v5
	v_sub_f32_e32 v2, v2, v16
	v_sub_f32_e32 v5, v5, v10
	v_add_f32_e32 v2, v3, v2
	v_add_f32_e32 v2, v5, v2
	v_add_f32_e32 v3, v21, v2
	v_mul_f32_e32 v5, v8, v3
	v_sub_f32_e32 v10, v21, v3
	v_mul_f32_e32 v16, v7, v5
	v_add_f32_e32 v2, v2, v10
	v_add_f32_e32 v10, v4, v5
	v_fma_f32 v7, v5, v7, -v16
	v_sub_f32_e32 v4, v10, v4
	v_fmac_f32_e32 v7, v5, v1
	v_sub_f32_e32 v1, v5, v4
	v_add_f32_e32 v4, v16, v7
	v_sub_f32_e32 v5, v4, v16
	v_sub_f32_e32 v16, v3, v4
	v_sub_f32_e32 v3, v3, v16
	v_sub_f32_e32 v3, v3, v4
	v_cvt_f32_i32_e32 v0, v0
	v_sub_f32_e32 v5, v5, v7
	v_add_f32_e32 v2, v2, v3
	v_add_f32_e32 v2, v5, v2
	v_add_f32_e32 v2, v16, v2
	v_mul_f32_e32 v2, v8, v2
	v_mul_f32_e32 v6, 0x3f317218, v0
	v_add_f32_e32 v1, v1, v2
	v_add_f32_e32 v2, v10, v1
	v_fma_f32 v5, v0, s81, -v6
	v_fmac_f32_e32 v5, 0xb102e308, v0
	v_sub_f32_e32 v0, v2, v10
	v_mul_f32_e32 v3, v2, v2
	v_sub_f32_e32 v0, v1, v0
	v_add_f32_e32 v1, v6, v5
	v_fmamk_f32 v4, v3, 0x3e9b6dac, v200
	v_sub_f32_e32 v6, v1, v6
	v_fmaak_f32 v4, v3, v4, 0x3f2aaada
	v_sub_f32_e32 v5, v5, v6
	v_ldexp_f32 v6, v2, 1
	v_mul_f32_e32 v2, v2, v3
	v_mul_f32_e32 v2, v2, v4
	v_add_f32_e32 v3, v6, v2
	v_sub_f32_e32 v4, v3, v6
	v_ldexp_f32 v0, v0, 1
	v_sub_f32_e32 v2, v2, v4
	v_add_f32_e32 v0, v0, v2
	v_add_f32_e32 v2, v3, v0
	v_sub_f32_e32 v3, v2, v3
	v_sub_f32_e32 v0, v0, v3
	v_add_f32_e32 v3, v1, v2
	v_sub_f32_e32 v4, v3, v1
	v_sub_f32_e32 v6, v3, v4
	v_sub_f32_e32 v1, v1, v6
	v_sub_f32_e32 v2, v2, v4
	v_add_f32_e32 v1, v2, v1
	v_add_f32_e32 v2, v5, v0
	v_sub_f32_e32 v4, v2, v5
	v_add_f32_e32 v1, v2, v1
	v_sub_f32_e32 v6, v2, v4
	v_add_f32_e32 v2, v3, v1
	v_sub_f32_e32 v5, v5, v6
	v_sub_f32_e32 v0, v0, v4
	v_sub_f32_e32 v3, v2, v3
	v_add_f32_e32 v0, v0, v5
	v_sub_f32_e32 v1, v1, v3
	v_add_f32_e32 v0, v0, v1
	v_add_f32_e32 v0, v2, v0
	v_cmp_neq_f32_e32 vcc, s91, v11
	v_mov_b32_e32 v1, v65
	v_mul_lo_u32 v115, v64, s30
	v_cndmask_b32_e32 v0, v201, v0, vcc
	v_cmp_ngt_f32_e32 vcc, -1.0, v11
	v_mul_lo_u32 v206, v39, s87
	v_mul_lo_u32 v210, v64, s87
	v_cndmask_b32_e32 v0, v202, v0, vcc
	v_cmp_neq_f32_e32 vcc, -1.0, v11
	v_ashrrev_i32_e32 v39, 31, v38
	v_sub_u32_e32 v41, 0xfe, v37
	v_cndmask_b32_e32 v0, v203, v0, vcc
	v_cmp_lt_f32_e64 vcc, |v11|, s92
	v_mul_lo_u32 v59, v41, s89
	v_mul_lo_u32 v60, v41, s30
	v_cndmask_b32_e32 v6, v0, v11, vcc
	v_lshlrev_b32_e32 v2, 4, v32
	v_and_b32_e32 v2, 0x70, v2
	v_lshlrev_b32_e32 v1, 2, v15
	v_add_u32_e32 v45, s95, v2
	v_or3_b32 v2, v19, v20, s0
	s_and_b32 s0, s4, 0x3fffffc0
	v_add_u32_e32 v161, s94, v1
	s_cmp_eq_u32 s6, 7
	v_lshl_add_u32 v254, s0, 2, v161
	s_cselect_b64 s[0:1], -1, 0
	s_cmp_eq_u32 s6, 6
	s_cselect_b64 s[16:17], -1, 0
	s_cmp_eq_u32 s6, 5
	s_cselect_b64 s[4:5], -1, 0
	s_cmp_eq_u32 s6, 4
	s_cselect_b64 s[8:9], -1, 0
	s_cmp_eq_u32 s6, 3
	s_cselect_b64 s[10:11], -1, 0
	s_cmp_eq_u32 s6, 2
	s_cselect_b64 s[12:13], -1, 0
	s_cmp_eq_u32 s6, 1
	s_cselect_b64 s[14:15], -1, 0
	s_lshl_b32 s6, s25, 7
	s_and_b32 s6, s6, 0xe00
	s_lshl_b32 s7, s29, 7
	s_or_b32 s6, s7, s6
	s_add_u32 s6, s6, s44
	v_add_u32_e32 v50, s95, v1
	v_add_u32_e32 v1, 0x400, v32
	s_addc_u32 s7, 0, s45
	v_ashrrev_i32_e32 v40, 3, v1
	v_add_u32_e32 v1, 0x600, v32
	v_and_b32_e32 v32, 7, v32
	s_add_u32 s18, s84, s46
	v_lshlrev_b32_e32 v64, 4, v32
	v_lshl_or_b32 v32, v33, 10, v34
	v_mov_b32_e32 v33, v65
	s_addc_u32 s19, s85, s47
	v_lshl_add_u64 v[144:145], v[32:33], 1, s[18:19]
	v_lshlrev_b64 v[32:33], 12, v[38:39]
	v_lshl_add_u64 v[32:33], s[6:7], 0, v[32:33]
	v_mul_lo_u32 v207, v41, s87
	v_lshl_add_u64 v[32:33], v[32:33], 0, v[64:65]
	v_ashrrev_i32_e32 v41, 31, v40
	v_or_b32_e32 v43, 2, v37
	v_lshl_add_u64 v[252:253], s[42:43], 0, v[32:33]
	v_lshlrev_b64 v[32:33], 12, v[40:41]
	v_ashrrev_i32_e32 v42, 3, v1
	v_sub_u32_e32 v43, 0xff, v43
	v_or_b32_e32 v63, 3, v37
	v_or_b32_e32 v66, 5, v37
	v_or_b32_e32 v67, 6, v37
	v_or_b32_e32 v120, 7, v37
	v_or_b32_e32 v123, 8, v37
	v_or_b32_e32 v126, 9, v37
	v_or_b32_e32 v129, 10, v37
	v_or_b32_e32 v132, 11, v37
	v_or_b32_e32 v135, 12, v37
	v_or_b32_e32 v142, 13, v37
	v_or_b32_e32 v143, 14, v37
	v_or_b32_e32 v37, 15, v37
	v_lshl_add_u64 v[32:33], s[6:7], 0, v[32:33]
	v_mul_lo_u32 v61, v43, s89
	v_mul_lo_u32 v62, v43, s30
	v_sub_u32_e32 v37, 0xff, v37
	v_mul_lo_u32 v208, v43, s87
	v_lshl_add_u64 v[32:33], v[32:33], 0, v[64:65]
	v_ashrrev_i32_e32 v43, 31, v42
	v_sub_u32_e32 v2, 0xff, v2
	v_mul_lo_u32 v204, v37, s89
	v_mul_lo_u32 v205, v37, s30
	v_mul_lo_u32 v221, v37, s87
	v_ashrrev_i32_e32 v37, 31, v36
	v_lshl_add_u64 v[154:155], s[42:43], 0, v[32:33]
	v_lshlrev_b64 v[32:33], 12, v[42:43]
	v_mul_lo_u32 v2, v2, s89
	v_mul_lo_u32 v53, v36, s30
	v_sub_u32_e32 v63, 0xff, v63
	v_sub_u32_e32 v66, 0xff, v66
	v_sub_u32_e32 v67, 0xff, v67
	v_sub_u32_e32 v120, 0xff, v120
	v_sub_u32_e32 v123, 0xff, v123
	v_sub_u32_e32 v126, 0xff, v126
	v_lshlrev_b64 v[36:37], 12, v[36:37]
	v_lshl_add_u64 v[32:33], s[6:7], 0, v[32:33]
	v_lshlrev_b32_e32 v35, 5, v12
	v_add_u32_e32 v47, 0, v2
	v_mov_b32_e32 v2, s88
	v_lshl_add_u32 v49, v17, 1, 0
	v_lshl_add_u32 v51, v15, 1, s86
	v_mul_lo_u32 v112, v63, s89
	v_mul_lo_u32 v113, v63, s30
	v_mul_lo_u32 v116, v66, s89
	v_mul_lo_u32 v117, v66, s30
	v_mul_lo_u32 v118, v67, s89
	v_mul_lo_u32 v119, v67, s30
	v_mul_lo_u32 v121, v120, s89
	v_mul_lo_u32 v122, v120, s30
	v_mul_lo_u32 v124, v123, s89
	v_mul_lo_u32 v125, v123, s30
	v_mul_lo_u32 v127, v126, s89
	v_mul_lo_u32 v128, v126, s30
	v_sub_u32_e32 v129, 0xff, v129
	v_sub_u32_e32 v132, 0xff, v132
	v_sub_u32_e32 v135, 0xff, v135
	v_sub_u32_e32 v142, 0xff, v142
	v_sub_u32_e32 v143, 0xff, v143
	v_mul_lo_u32 v211, v66, s87
	v_mul_lo_u32 v212, v67, s87
	v_mul_lo_u32 v120, v120, s87
	v_mul_lo_u32 v123, v123, s87
	v_mul_lo_u32 v126, v126, s87
	v_lshl_add_u64 v[36:37], s[6:7], 0, v[36:37]
	v_lshl_add_u64 v[32:33], v[32:33], 0, v[64:65]
	v_mov_b32_e32 v66, v65
	v_mov_b32_e32 v67, v65
	s_waitcnt vmcnt(12)
; #define LAS __attribute__((address_space(3)))
; template <int dir>
; __device__ __forceinline__ void lru_pass(LAS unsigned char* lds, const Params& P, int b, int h, int q, bool dry) {
;     ...
;         const float br = -LOG2E * P.lru_ba[(dir * 8 + h) * 128 + chl], bi = -LOG2E * P.lru_bx[(dir * 8 + h) * 128 + chl];
;         const float lam = P.lru_lambda[dir * 1024 + ch];
;         const float cl = -8.0f * LOG2E * log1pf(__expf(-lam));
;         float carry = 0.f;
;         LruTile cur = lru_tile(Z, ZC, b, h, dir, 0);
;         u32x4 rows[11];
;         constexpr int NIN = dir == 0 ? 2 : 4;
;         u32x4 inr[NIN];
;         lru_load_rows(rows, cur, tr, cgp);
; #pragma unroll
;         for (int i = 0; i < NIN; ++i) inr[i] = (u32x4){0u, 0u, 0u, 0u};
;         int t0_prev = 0;
;     ...
;             f32x16 zr, zi;
; #pragma unroll
;             for (int v = 0; v < 16; ++v) { zr[v] = br; zi[v] = bi; }
;             const int sbase = 32 * wid + 16 * g;
;             { const int sl = 32 * wid + s_i; const int tlA = dir == 0 ? sl : 255 - sl;
;               const LAS unsigned char* ap = XC + tlA * XC_PITCH + 16 * g;
;               const LAS unsigned char* wrp = WB + nl * XC_PITCH + 16 * g; const LAS unsigned char* wip = wrp + 32 * XC_PITCH;
; #pragma unroll
;               for (int ks = 0; ks < 8; ++ks) { const bf16x8 A = *(const LAS bf16x8*)(ap + 32 * ks);
;                   const bf16x8 Br = *(const LAS bf16x8*)(wrp + 32 * ks), Bi = *(const LAS bf16x8*)(wip + 32 * ks);
;                   zr = __builtin_amdgcn_mfma_f32_32x32x16_bf16(A, Br, zr, 0, 0, 0); zi = __builtin_amdgcn_mfma_f32_32x32x16_bf16(A, Bi, zi, 0, 0, 0); } }
;             unsigned xcb[16], pk[16];
; #pragma unroll
;             for (int v = 0; v < 16; ++v) { const int s = sbase + v; const int tl = dir == 0 ? s : 255 - s; xcb[v] = *(const LAS bf16_t*)(XC + tl * XC_PITCH + chl * 2);
;                 if (dir == 0) pk[v] = *(const LAS bf16_t*)(TIN + tl * IO_NP + nl * 2); else pk[v] = *(const LAS unsigned*)(TIN + tl * IO_WP + nl * 4); }
	v_mul_f32_e32 v0, 0xbfb8aa3b, v14
	s_waitcnt vmcnt(11)
	v_mul_f32_e32 v16, 0xbfb8aa3b, v9
	v_mad_u32_u24 v48, v15, s89, v2
	v_mul_lo_u32 v54, v38, s30
	v_mul_lo_u32 v55, v40, s30
	v_mul_lo_u32 v56, v42, s30
	v_ashrrev_i32_e32 v138, 2, v13
	v_mul_lo_u32 v130, v129, s89
	v_mul_lo_u32 v131, v129, s30
	v_mul_lo_u32 v133, v132, s89
	v_mul_lo_u32 v134, v132, s30
	v_mul_lo_u32 v146, v135, s89
	v_mul_lo_u32 v147, v135, s30
	v_mul_lo_u32 v148, v142, s89
	v_mul_lo_u32 v149, v142, s30
	v_mul_lo_u32 v162, v143, s89
	v_mul_lo_u32 v163, v143, s30
	v_mul_lo_u32 v63, v63, s87
	v_mul_lo_u32 v129, v129, s87
	v_mul_lo_u32 v132, v132, s87
	v_mul_lo_u32 v135, v135, s87
	v_mul_lo_u32 v219, v142, s87
	v_mul_lo_u32 v220, v143, s87
	v_lshl_add_u64 v[36:37], v[36:37], 0, v[64:65]
	v_lshl_add_u64 v[150:151], s[42:43], 0, v[32:33]
	v_mov_b32_e32 v64, v65
	v_add_u32_e32 v32, 0, v35
	v_add_u32_e32 v180, v49, v112
	v_add_u32_e32 v181, v50, v113
	v_add_u32_e32 v182, v49, v114
	v_add_u32_e32 v183, v50, v115
	v_add_u32_e32 v184, v49, v116
	v_add_u32_e32 v185, v50, v117
	v_add_u32_e32 v186, v49, v118
	v_add_u32_e32 v187, v50, v119
	v_add_u32_e32 v188, v49, v121
	v_add_u32_e32 v189, v50, v122
	v_add_u32_e32 v190, v49, v124
	v_add_u32_e32 v191, v50, v125
	v_add_u32_e32 v192, v49, v127
	v_add_u32_e32 v213, v51, v120
	v_add_u32_e32 v214, v51, v123
	v_add_u32_e32 v215, v51, v126
	v_mov_b64_e32 v[114:115], v[66:67]
	v_mov_b64_e32 v[118:119], v[66:67]
	v_mov_b64_e32 v[122:123], v[66:67]
	v_mov_b64_e32 v[126:127], v[66:67]
	s_mov_b32 s78, 0
	v_mov_b32_e32 v156, 0xff800000
	v_mul_f32_e32 v159, 0xc138aa3b, v6
	v_cmp_eq_u32_e32 vcc, 0, v18
	v_mul_lo_u32 v164, v140, s87
	v_ashrrev_i32_e32 v141, 31, v140
	v_mul_lo_u32 v152, v138, s87
	v_ashrrev_i32_e32 v139, 31, v138
	v_mov_b32_e32 v1, v0
	v_mov_b32_e32 v2, v0
	v_mov_b32_e32 v3, v0
	v_mov_b32_e32 v4, v0
	v_mov_b32_e32 v5, v0
	v_mov_b32_e32 v6, v0
	v_mov_b32_e32 v7, v0
	v_mov_b32_e32 v8, v0
	v_mov_b32_e32 v9, v0
	v_mov_b32_e32 v10, v0
	v_mov_b32_e32 v11, v0
	v_mov_b32_e32 v12, v0
	v_mov_b32_e32 v13, v0
	v_mov_b32_e32 v14, v0
	v_mov_b32_e32 v15, v0
	v_mov_b32_e32 v17, v16
	v_mov_b32_e32 v18, v16
	v_mov_b32_e32 v19, v16
	v_mov_b32_e32 v20, v16
	v_mov_b32_e32 v21, v16
	v_mov_b32_e32 v22, v16
	v_mov_b32_e32 v23, v16
	v_mov_b32_e32 v24, v16
	v_mov_b32_e32 v25, v16
	v_mov_b32_e32 v26, v16
	v_mov_b32_e32 v27, v16
	v_mov_b32_e32 v28, v16
	v_mov_b32_e32 v29, v16
	v_mov_b32_e32 v30, v16
	v_mov_b32_e32 v31, v16
	v_lshl_add_u64 v[142:143], s[42:43], 0, v[36:37]
	s_movk_i32 s28, 0x100
	v_mov_b32_e32 v222, 0
	s_mov_b64 s[44:45], 0
	s_movk_i32 s25, 0x700
	v_add_u32_e32 v165, 0x15c00, v32
	v_add_u32_e32 v166, v44, v52
	v_add_u32_e32 v168, v45, v53
	v_add_u32_e32 v169, v45, v54
	v_add_u32_e32 v170, v45, v55
	v_add_u32_e32 v171, v45, v56
	v_add_u32_e32 v172, v47, v46
	v_add_u32_e32 v173, v48, v46
	v_add_u32_e32 v174, v49, v57
	v_add_u32_e32 v175, v50, v58
	v_add_u32_e32 v176, v49, v59
	v_add_u32_e32 v177, v50, v60
	v_add_u32_e32 v178, v49, v61
	v_add_u32_e32 v179, v50, v62
	v_add_u32_e32 v193, v50, v128
	v_add_u32_e32 v194, v49, v130
	v_add_u32_e32 v195, v50, v131
	v_add_u32_e32 v196, v49, v133
	v_add_u32_e32 v197, v50, v134
	v_add_u32_e32 v198, v49, v146
	v_add_u32_e32 v199, v50, v147
	v_add_u32_e32 v200, v49, v148
	v_add_u32_e32 v201, v50, v149
	v_add_u32_e32 v202, v49, v162
	v_add_u32_e32 v203, v50, v163
	v_add_u32_e32 v204, v49, v204
	v_add_u32_e32 v205, v50, v205
	v_add_u32_e32 v206, v51, v206
	v_add_u32_e32 v207, v51, v207
	v_add_u32_e32 v208, v51, v208
	v_add_u32_e32 v209, v51, v63
	v_add_u32_e32 v210, v51, v210
	v_add_u32_e32 v211, v51, v211
	v_add_u32_e32 v212, v51, v212
	v_add_u32_e32 v216, v51, v129
	v_add_u32_e32 v217, v51, v132
	v_add_u32_e32 v218, v51, v135
	v_add_u32_e32 v219, v51, v219
	v_add_u32_e32 v220, v51, v220
	v_add_u32_e32 v221, v51, v221
	v_mov_b64_e32 v[112:113], v[64:65]
	v_mov_b64_e32 v[116:117], v[64:65]
	v_mov_b64_e32 v[120:121], v[64:65]
	v_mov_b64_e32 v[124:125], v[64:65]
	s_mov_b32 s46, 0
	s_mov_b32 s29, 0
	v_lshrrev_b32_e32 v32, 8, v167
	v_mul_u32_u24_e32 v33, 0x3600, v32
	v_add_u32_e32 v168, v168, v33
	v_add_u32_e32 v169, v169, v33
	v_add_u32_e32 v170, v170, v33
	v_add_u32_e32 v171, v171, v33
	v_add_u32_e32 v169, 0xffffee00, v169
	v_add_u32_e32 v170, 0xffffdc00, v170
	v_add_u32_e32 v171, 0xffffca00, v171
	v_mul_u32_u24_e32 v66, 0x60000, v32
	v_mov_b32_e32 v67, 0
	v_lshl_add_u64 v[142:143], v[66:67], 0, v[142:143]
	v_lshl_add_u64 v[252:253], v[66:67], 0, v[252:253]
	v_lshl_add_u64 v[154:155], v[66:67], 0, v[154:155]
	v_lshl_add_u64 v[150:151], v[66:67], 0, v[150:151]
	s_mov_b32 s19, -1
	s_mov_b32 s18, 0xfffe0000
	v_lshl_add_u64 v[252:253], v[252:253], 0, s[18:19]
	s_mov_b32 s18, 0xfffc0000
	v_lshl_add_u64 v[154:155], v[154:155], 0, s[18:19]
	s_mov_b32 s18, 0xfffa0000
	v_lshl_add_u64 v[150:151], v[150:151], 0, s[18:19]
	v_mul_u32_u24_e32 v33, 0x1400, v32
	v_add_u32_e32 v164, v164, v33
	v_add_u32_e32 v152, v152, v33
	v_add_u32_e32 v152, 0xffffec00, v152
	v_lshlrev_b32_e32 v33, 6, v32
	v_add_u32_e32 v140, v140, v33
	v_add_u32_e32 v138, v138, v33
	v_add_u32_e32 v138, 0xffffffc0, v138
	v_lshrrev_b32_e32 v33, 6, v167
	s_nop 1
	v_readfirstlane_b32 s18, v33
	s_lshl_b32 s19, s18, 6
	s_sub_i32 s19, s19, 0xe0
	s_mul_i32 s20, s19, 0x110
	v_add_u32_e32 v172, s20, v172
	v_add_u32_e32 v174, s20, v174
	v_add_u32_e32 v176, s20, v176
	v_add_u32_e32 v178, s20, v178
	v_add_u32_e32 v180, s20, v180
	v_add_u32_e32 v182, s20, v182
	v_add_u32_e32 v184, s20, v184
	v_add_u32_e32 v186, s20, v186
	v_add_u32_e32 v188, s20, v188
	v_add_u32_e32 v190, s20, v190
	v_add_u32_e32 v192, s20, v192
	v_add_u32_e32 v194, s20, v194
	v_add_u32_e32 v196, s20, v196
; #define LAS __attribute__((address_space(3)))
; __device__ __forceinline__ unsigned cvt_pk_bf16(float lo, float hi) { unsigned r; asm volatile("v_cvt_pk_bf16_f32 %0, %1, %2" : "=v"(r) : "v"(lo), "v"(hi)); return r; }
; __device__ __forceinline__ float bf_lo(unsigned u) { return __uint_as_float(u << 16); }
; __device__ __forceinline__ float bf_hi(unsigned u) { return __uint_as_float(u & 0xffff0000u); }
; template <int dir>
; __device__ __forceinline__ void lru_pass(LAS unsigned char* lds, const Params& P, int b, int h, int q, bool dry) {
;     ...
;         for (int sc = 0; sc < 9; ++sc) {
;             const bool isctx = (sc == 0);
;             const int t0 = cur.t0;
; #pragma unroll
;             for (int j = 0; j < 11; ++j) { if (j != 0 && j < 9) continue;
;                 const int t = t0 + tr * 8 - 1 + j; if (t < 0 || t >= cur.L) rows[j] = (u32x4){0u, 0u, 0u, 0u}; }
;             f32x2 cw2[4][4], cb2[4];
; #pragma unroll
;             for (int k = 0; k < 5; ++k) { const f32x4 a = *(const LAS f32x4*)(CWL + k * 128 + cgp * 8), c2 = *(const LAS f32x4*)(CWL + k * 128 + cgp * 8 + 4);
;                 if (k < 4) { cw2[k][0] = (f32x2){a[0], a[1]}; cw2[k][1] = (f32x2){a[2], a[3]}; cw2[k][2] = (f32x2){c2[0], c2[1]}; cw2[k][3] = (f32x2){c2[2], c2[3]}; }
;                 else { cb2[0] = (f32x2){a[0], a[1]}; cb2[1] = (f32x2){a[2], a[3]}; cb2[2] = (f32x2){c2[0], c2[1]}; cb2[3] = (f32x2){c2[2], c2[3]}; } }
; #pragma unroll
;             for (int j = 0; j < 8; ++j) {
;                 f32x2 o0 = cb2[0], o1 = cb2[1], o2 = cb2[2], o3 = cb2[3];
; #pragma unroll
;                 for (int k = 0; k < 4; ++k) { const u32x4 rr = rows[j + k];
;                     o0 = cw2[k][0] * (f32x2){bf_lo(rr.x), bf_hi(rr.x)} + o0; o1 = cw2[k][1] * (f32x2){bf_lo(rr.y), bf_hi(rr.y)} + o1;
;                     o2 = cw2[k][2] * (f32x2){bf_lo(rr.z), bf_hi(rr.z)} + o2; o3 = cw2[k][3] * (f32x2){bf_lo(rr.w), bf_hi(rr.w)} + o3; }
;                 u32x4 w; w.x = cvt_pk_bf16(o0[0], o0[1]); w.y = cvt_pk_bf16(o1[0], o1[1]); w.z = cvt_pk_bf16(o2[0], o2[1]); w.w = cvt_pk_bf16(o3[0], o3[1]);
;                 *(LAS u32x4*)(XC + (tr * 8 + j) * XC_PITCH + cgp * 16) = w;
;             }
	v_add_u32_e32 v198, s20, v198
	v_add_u32_e32 v200, s20, v200
	v_add_u32_e32 v202, s20, v202
	v_add_u32_e32 v204, s20, v204
	s_mul_i32 s20, s19, 0x90
	v_add_u32_e32 v175, s20, v175
	v_add_u32_e32 v177, s20, v177
	v_add_u32_e32 v179, s20, v179
	v_add_u32_e32 v181, s20, v181
	v_add_u32_e32 v183, s20, v183
	v_add_u32_e32 v185, s20, v185
	v_add_u32_e32 v187, s20, v187
	v_add_u32_e32 v189, s20, v189
	v_add_u32_e32 v191, s20, v191
	v_add_u32_e32 v193, s20, v193
	v_add_u32_e32 v195, s20, v195
	v_add_u32_e32 v197, s20, v197
	v_add_u32_e32 v199, s20, v199
	v_add_u32_e32 v201, s20, v201
	v_add_u32_e32 v203, s20, v203
	v_add_u32_e32 v205, s20, v205
	s_mul_i32 s20, s19, 0x50
	v_add_u32_e32 v206, s20, v206
	v_add_u32_e32 v207, s20, v207
	v_add_u32_e32 v208, s20, v208
	v_add_u32_e32 v209, s20, v209
	v_add_u32_e32 v210, s20, v210
	v_add_u32_e32 v211, s20, v211
	v_add_u32_e32 v212, s20, v212
	v_add_u32_e32 v213, s20, v213
	v_add_u32_e32 v214, s20, v214
	v_add_u32_e32 v215, s20, v215
	v_add_u32_e32 v216, s20, v216
	v_add_u32_e32 v217, s20, v217
	v_add_u32_e32 v218, s20, v218
	v_add_u32_e32 v219, s20, v219
	v_add_u32_e32 v220, s20, v220
	v_add_u32_e32 v221, s20, v221
	s_lshl_b32 s20, s18, 1
	s_sub_i32 s20, 7, s20
	s_lshl_b32 s20, s20, 8
	v_add_u32_e32 v254, s20, v254
	s_sub_i32 s18, 7, s18
	s_lshr_b32 s101, s18, 2
	s_or_b32 s19, s18, 4
	s_cmp_eq_u32 s19, 7
	s_cselect_b64 s[0:1], -1, 0
	s_cmp_eq_u32 s19, 6
	s_cselect_b64 s[16:17], -1, 0
	s_cmp_eq_u32 s19, 5
	s_cselect_b64 s[4:5], -1, 0
	s_cmp_eq_u32 s19, 4
	s_cselect_b64 s[8:9], -1, 0
	s_cmp_eq_u32 s19, 3
	s_cselect_b64 s[10:11], -1, 0
	s_cmp_eq_u32 s19, 2
	s_cselect_b64 s[12:13], -1, 0
	s_cmp_eq_u32 s19, 1
	s_cselect_b64 s[14:15], -1, 0
	s_mov_b32 s98, 0
	s_cmp_eq_u32 s101, 0
	s_cselect_b32 s99, 0x14400, 0
	s_cselect_b32 s100, 0, 0x400
	v_add_u32_e32 v33, 0x14000, v254
	v_mov_b32_e32 v66, 1.0
	v_mov_b32_e32 v67, 0
	ds_write2_b32 v33, v66, v67 offset1:32
	s_mov_b32 s40, 0x8000000
	s_mov_b32 s41, 0
	s_lshr_b32 s18, s2, 5
	s_lshl_b32 s18, s18, 3
	s_and_b32 s19, s2, 7
	s_or_b32 s18, s18, s19
	s_lshl_b32 s18, s18, 8
	s_add_u32 s18, s18, 0x84008
	s_add_u32 s18, s22, s18
	s_addc_u32 s19, s23, 0
	v_mov_b32_e32 v32, 0
	s_mov_b32 s21, 0x100000
.Lpc_spin:
	global_load_dword v33, v32, s[18:19] sc1
	s_waitcnt vmcnt(0)
	v_readfirstlane_b32 s20, v33
	s_cmp_ge_u32 s20, 4
	s_cbranch_scc1 .Lpc_done
	s_sleep 1
	s_add_i32 s21, s21, -1
	s_cmp_eq_u32 s21, 0
	s_cbranch_scc0 .Lpc_spin
.Lpc_done:
	s_cmp_eq_u32 s101, 0
	s_cbranch_scc1 .Lpp_b_nox
	s_waitcnt lgkmcnt(0)
	s_barrier
.Lpp_b_nox:
.LBB0_306:
	s_cmp_eq_u32 s46, 0
	s_cbranch_scc0 .Lpc_newA
	v_add_u32_e32 v32, s29, v160
	v_cmp_lt_i32_e64 s[18:19], -1, v32
	v_cmp_gt_i32_e64 s[20:21], s28, v32
	s_and_b64 s[18:19], s[18:19], s[20:21]
	v_add_u32_e32 v33, 9, v32
	s_waitcnt vmcnt(10)
	v_cndmask_b32_e64 v71, 0, v71, s[18:19]
	v_cndmask_b32_e64 v70, 0, v70, s[18:19]
	v_cndmask_b32_e64 v69, 0, v69, s[18:19]
	v_cndmask_b32_e64 v68, 0, v68, s[18:19]
	v_cmp_lt_i32_e64 s[18:19], -10, v32
	v_cmp_gt_i32_e64 s[20:21], s28, v33
	s_and_b64 s[18:19], s[18:19], s[20:21]
	v_add_u32_e32 v33, 10, v32
	s_waitcnt vmcnt(1)
	v_cndmask_b32_e64 v107, 0, v107, s[18:19]
	v_cndmask_b32_e64 v106, 0, v106, s[18:19]
	v_cndmask_b32_e64 v105, 0, v105, s[18:19]
	v_cndmask_b32_e64 v104, 0, v104, s[18:19]
	v_cmp_lt_i32_e64 s[18:19], -11, v32
	v_cmp_gt_i32_e64 s[20:21], s28, v33
	ds_read_b128 v[60:63], v165
	ds_read_b128 v[52:55], v165 offset:16
	ds_read_b128 v[44:47], v165 offset:528
	ds_read_b128 v[56:59], v165 offset:512
	ds_read_b128 v[40:43], v165 offset:1040
	ds_read_b128 v[48:51], v165 offset:1024
	ds_read_b128 v[128:131], v165 offset:2064
	ds_read_b128 v[132:135], v165 offset:2048
	ds_read_b128 v[32:35], v165 offset:1552
	ds_read_b128 v[36:39], v165 offset:1536
	v_lshlrev_b32_e32 v66, 16, v68
	v_and_b32_e32 v67, 0xffff0000, v68
	v_lshlrev_b32_e32 v148, 16, v70
	v_and_b32_e32 v149, 0xffff0000, v70
	s_waitcnt lgkmcnt(2)
	v_pk_fma_f32 v[66:67], v[60:61], v[66:67], v[132:133]
	v_lshlrev_b32_e32 v146, 16, v69
	v_and_b32_e32 v147, 0xffff0000, v69
	v_pk_fma_f32 v[148:149], v[52:53], v[148:149], v[128:129]
	v_lshlrev_b32_e32 v224, 16, v71
	v_and_b32_e32 v225, 0xffff0000, v71
	v_lshlrev_b32_e32 v228, 16, v72
	v_and_b32_e32 v229, 0xffff0000, v72
	v_lshlrev_b32_e32 v232, 16, v74
	v_and_b32_e32 v233, 0xffff0000, v74
	v_pk_fma_f32 v[146:147], v[62:63], v[146:147], v[134:135]
	v_pk_fma_f32 v[224:225], v[54:55], v[224:225], v[130:131]
	v_pk_fma_f32 v[66:67], v[56:57], v[228:229], v[66:67]
	v_lshlrev_b32_e32 v230, 16, v73
	v_and_b32_e32 v231, 0xffff0000, v73
	v_pk_fma_f32 v[148:149], v[44:45], v[232:233], v[148:149]
	v_lshlrev_b32_e32 v234, 16, v75
	v_and_b32_e32 v235, 0xffff0000, v75
	v_lshlrev_b32_e32 v236, 16, v76
	v_and_b32_e32 v237, 0xffff0000, v76
	v_lshlrev_b32_e32 v240, 16, v78
	v_and_b32_e32 v241, 0xffff0000, v78
	v_pk_fma_f32 v[146:147], v[58:59], v[230:231], v[146:147]
	v_pk_fma_f32 v[224:225], v[46:47], v[234:235], v[224:225]
	v_pk_fma_f32 v[66:67], v[48:49], v[236:237], v[66:67]
	v_lshlrev_b32_e32 v238, 16, v77
	v_and_b32_e32 v239, 0xffff0000, v77
	v_pk_fma_f32 v[148:149], v[40:41], v[240:241], v[148:149]
	v_lshlrev_b32_e32 v242, 16, v79
	v_and_b32_e32 v243, 0xffff0000, v79
	v_lshlrev_b32_e32 v244, 16, v80
	v_and_b32_e32 v245, 0xffff0000, v80
	v_lshlrev_b32_e32 v248, 16, v82
	v_and_b32_e32 v249, 0xffff0000, v82
	v_pk_fma_f32 v[146:147], v[50:51], v[238:239], v[146:147]
	v_pk_fma_f32 v[224:225], v[42:43], v[242:243], v[224:225]
	s_waitcnt lgkmcnt(0)
; #define LAS __attribute__((address_space(3)))
; __device__ __forceinline__ unsigned cvt_pk_bf16(float lo, float hi) { unsigned r; asm volatile("v_cvt_pk_bf16_f32 %0, %1, %2" : "=v"(r) : "v"(lo), "v"(hi)); return r; }
; __device__ __forceinline__ float bf_lo(unsigned u) { return __uint_as_float(u << 16); }
; __device__ __forceinline__ float bf_hi(unsigned u) { return __uint_as_float(u & 0xffff0000u); }
; template <int dir>
; __device__ __forceinline__ void lru_pass(LAS unsigned char* lds, const Params& P, int b, int h, int q, bool dry) {
;     ...
;             for (int j = 0; j < 8; ++j) {
;                 f32x2 o0 = cb2[0], o1 = cb2[1], o2 = cb2[2], o3 = cb2[3];
; #pragma unroll
;                 for (int k = 0; k < 4; ++k) { const u32x4 rr = rows[j + k];
;                     o0 = cw2[k][0] * (f32x2){bf_lo(rr.x), bf_hi(rr.x)} + o0; o1 = cw2[k][1] * (f32x2){bf_lo(rr.y), bf_hi(rr.y)} + o1;
;                     o2 = cw2[k][2] * (f32x2){bf_lo(rr.z), bf_hi(rr.z)} + o2; o3 = cw2[k][3] * (f32x2){bf_lo(rr.w), bf_hi(rr.w)} + o3; }
;                 u32x4 w; w.x = cvt_pk_bf16(o0[0], o0[1]); w.y = cvt_pk_bf16(o1[0], o1[1]); w.z = cvt_pk_bf16(o2[0], o2[1]); w.w = cvt_pk_bf16(o3[0], o3[1]);
;                 *(LAS u32x4*)(XC + (tr * 8 + j) * XC_PITCH + cgp * 16) = w;
;             }
	v_pk_fma_f32 v[66:67], v[36:37], v[244:245], v[66:67]
	v_lshlrev_b32_e32 v246, 16, v81
	v_and_b32_e32 v247, 0xffff0000, v81
	v_pk_fma_f32 v[148:149], v[32:33], v[248:249], v[148:149]
	v_lshlrev_b32_e32 v250, 16, v83
	v_and_b32_e32 v251, 0xffff0000, v83
	v_pk_fma_f32 v[146:147], v[38:39], v[246:247], v[146:147]
	v_pk_fma_f32 v[162:163], v[34:35], v[250:251], v[224:225]
	v_cvt_pk_bf16_f32 v224, v66, v67
	v_cvt_pk_bf16_f32 v225, v146, v147
	v_cvt_pk_bf16_f32 v226, v148, v149
	v_pk_fma_f32 v[66:67], v[60:61], v[228:229], v[132:133]
	v_pk_fma_f32 v[148:149], v[52:53], v[232:233], v[128:129]
	v_pk_fma_f32 v[146:147], v[62:63], v[230:231], v[134:135]
	v_pk_fma_f32 v[66:67], v[56:57], v[236:237], v[66:67]
	v_pk_fma_f32 v[148:149], v[44:45], v[240:241], v[148:149]
	v_pk_fma_f32 v[146:147], v[58:59], v[238:239], v[146:147]
	v_pk_fma_f32 v[66:67], v[48:49], v[244:245], v[66:67]
	v_pk_fma_f32 v[148:149], v[40:41], v[248:249], v[148:149]
	v_lshlrev_b32_e32 v228, 16, v84
	v_and_b32_e32 v229, 0xffff0000, v84
	v_lshlrev_b32_e32 v232, 16, v86
	v_and_b32_e32 v233, 0xffff0000, v86
	v_cvt_pk_bf16_f32 v227, v162, v163
	v_pk_fma_f32 v[162:163], v[54:55], v[234:235], v[130:131]
	v_pk_fma_f32 v[146:147], v[50:51], v[246:247], v[146:147]
	v_pk_fma_f32 v[66:67], v[36:37], v[228:229], v[66:67]
	v_lshlrev_b32_e32 v230, 16, v85
	v_and_b32_e32 v231, 0xffff0000, v85
	v_pk_fma_f32 v[148:149], v[32:33], v[232:233], v[148:149]
	ds_write_b128 v166, v[224:227]
	v_pk_fma_f32 v[162:163], v[46:47], v[242:243], v[162:163]
	v_pk_fma_f32 v[146:147], v[38:39], v[230:231], v[146:147]
	v_cvt_pk_bf16_f32 v224, v66, v67
	v_pk_fma_f32 v[66:67], v[60:61], v[236:237], v[132:133]
	v_cvt_pk_bf16_f32 v225, v146, v147
	v_cvt_pk_bf16_f32 v226, v148, v149
	v_pk_fma_f32 v[148:149], v[52:53], v[240:241], v[128:129]
	v_pk_fma_f32 v[162:163], v[42:43], v[250:251], v[162:163]
	v_lshlrev_b32_e32 v234, 16, v87
	v_and_b32_e32 v235, 0xffff0000, v87
	v_pk_fma_f32 v[146:147], v[62:63], v[238:239], v[134:135]
	v_pk_fma_f32 v[66:67], v[56:57], v[244:245], v[66:67]
	v_pk_fma_f32 v[148:149], v[44:45], v[248:249], v[148:149]
	v_pk_fma_f32 v[162:163], v[34:35], v[234:235], v[162:163]
	v_pk_fma_f32 v[146:147], v[58:59], v[246:247], v[146:147]
	v_pk_fma_f32 v[66:67], v[48:49], v[228:229], v[66:67]
	v_pk_fma_f32 v[148:149], v[40:41], v[232:233], v[148:149]
	v_lshlrev_b32_e32 v236, 16, v88
	v_and_b32_e32 v237, 0xffff0000, v88
	v_lshlrev_b32_e32 v240, 16, v90
	v_and_b32_e32 v241, 0xffff0000, v90
	v_cvt_pk_bf16_f32 v227, v162, v163
	v_pk_fma_f32 v[162:163], v[54:55], v[242:243], v[130:131]
	v_pk_fma_f32 v[146:147], v[50:51], v[230:231], v[146:147]
	v_pk_fma_f32 v[66:67], v[36:37], v[236:237], v[66:67]
	v_lshlrev_b32_e32 v238, 16, v89
	v_and_b32_e32 v239, 0xffff0000, v89
	v_pk_fma_f32 v[148:149], v[32:33], v[240:241], v[148:149]
	ds_write_b128 v166, v[224:227] offset:272
	v_pk_fma_f32 v[162:163], v[46:47], v[250:251], v[162:163]
	v_pk_fma_f32 v[146:147], v[38:39], v[238:239], v[146:147]
	v_cvt_pk_bf16_f32 v224, v66, v67
	v_pk_fma_f32 v[66:67], v[60:61], v[244:245], v[132:133]
	v_cvt_pk_bf16_f32 v225, v146, v147
	v_cvt_pk_bf16_f32 v226, v148, v149
	v_pk_fma_f32 v[148:149], v[52:53], v[248:249], v[128:129]
	v_pk_fma_f32 v[162:163], v[42:43], v[234:235], v[162:163]
	v_lshlrev_b32_e32 v242, 16, v91
	v_and_b32_e32 v243, 0xffff0000, v91
	v_pk_fma_f32 v[146:147], v[62:63], v[246:247], v[134:135]
	v_pk_fma_f32 v[66:67], v[56:57], v[228:229], v[66:67]
	v_pk_fma_f32 v[148:149], v[44:45], v[232:233], v[148:149]
	v_pk_fma_f32 v[162:163], v[34:35], v[242:243], v[162:163]
	v_pk_fma_f32 v[146:147], v[58:59], v[230:231], v[146:147]
	v_pk_fma_f32 v[66:67], v[48:49], v[236:237], v[66:67]
	v_pk_fma_f32 v[148:149], v[40:41], v[240:241], v[148:149]
	v_lshlrev_b32_e32 v244, 16, v92
	v_and_b32_e32 v245, 0xffff0000, v92
	v_lshlrev_b32_e32 v248, 16, v94
	v_and_b32_e32 v249, 0xffff0000, v94
	v_cvt_pk_bf16_f32 v227, v162, v163
	v_pk_fma_f32 v[162:163], v[54:55], v[250:251], v[130:131]
	v_pk_fma_f32 v[146:147], v[50:51], v[238:239], v[146:147]
	v_pk_fma_f32 v[66:67], v[36:37], v[244:245], v[66:67]
	v_lshlrev_b32_e32 v246, 16, v93
	v_and_b32_e32 v247, 0xffff0000, v93
	v_pk_fma_f32 v[148:149], v[32:33], v[248:249], v[148:149]
	ds_write_b128 v166, v[224:227] offset:544
	v_pk_fma_f32 v[162:163], v[46:47], v[234:235], v[162:163]
	v_pk_fma_f32 v[146:147], v[38:39], v[246:247], v[146:147]
	v_cvt_pk_bf16_f32 v224, v66, v67
	v_pk_fma_f32 v[66:67], v[60:61], v[228:229], v[132:133]
	v_cvt_pk_bf16_f32 v225, v146, v147
	v_cvt_pk_bf16_f32 v226, v148, v149
	v_pk_fma_f32 v[148:149], v[52:53], v[232:233], v[128:129]
	v_pk_fma_f32 v[162:163], v[42:43], v[242:243], v[162:163]
	v_lshlrev_b32_e32 v250, 16, v95
	v_and_b32_e32 v251, 0xffff0000, v95
	v_pk_fma_f32 v[146:147], v[62:63], v[230:231], v[134:135]
	v_pk_fma_f32 v[66:67], v[56:57], v[236:237], v[66:67]
	v_pk_fma_f32 v[148:149], v[44:45], v[240:241], v[148:149]
	v_pk_fma_f32 v[162:163], v[34:35], v[250:251], v[162:163]
	v_pk_fma_f32 v[146:147], v[58:59], v[238:239], v[146:147]
	v_pk_fma_f32 v[66:67], v[48:49], v[244:245], v[66:67]
	v_pk_fma_f32 v[148:149], v[40:41], v[248:249], v[148:149]
	v_lshlrev_b32_e32 v228, 16, v96
	v_and_b32_e32 v229, 0xffff0000, v96
	v_lshlrev_b32_e32 v232, 16, v98
	v_and_b32_e32 v233, 0xffff0000, v98
	v_cvt_pk_bf16_f32 v227, v162, v163
	v_pk_fma_f32 v[162:163], v[54:55], v[234:235], v[130:131]
	v_pk_fma_f32 v[146:147], v[50:51], v[246:247], v[146:147]
	v_pk_fma_f32 v[66:67], v[36:37], v[228:229], v[66:67]
	v_lshlrev_b32_e32 v230, 16, v97
	v_and_b32_e32 v231, 0xffff0000, v97
	v_pk_fma_f32 v[148:149], v[32:33], v[232:233], v[148:149]
	ds_write_b128 v166, v[224:227] offset:816
; #define LAS __attribute__((address_space(3)))
; __device__ __forceinline__ unsigned cvt_pk_bf16(float lo, float hi) { unsigned r; asm volatile("v_cvt_pk_bf16_f32 %0, %1, %2" : "=v"(r) : "v"(lo), "v"(hi)); return r; }
; __device__ __forceinline__ float bf_lo(unsigned u) { return __uint_as_float(u << 16); }
; __device__ __forceinline__ float bf_hi(unsigned u) { return __uint_as_float(u & 0xffff0000u); }
; template <int dir>
; __device__ __forceinline__ void lru_pass(LAS unsigned char* lds, const Params& P, int b, int h, int q, bool dry) {
;     ...
;             for (int j = 0; j < 8; ++j) {
;                 f32x2 o0 = cb2[0], o1 = cb2[1], o2 = cb2[2], o3 = cb2[3];
; #pragma unroll
;                 for (int k = 0; k < 4; ++k) { const u32x4 rr = rows[j + k];
;                     o0 = cw2[k][0] * (f32x2){bf_lo(rr.x), bf_hi(rr.x)} + o0; o1 = cw2[k][1] * (f32x2){bf_lo(rr.y), bf_hi(rr.y)} + o1;
;                     o2 = cw2[k][2] * (f32x2){bf_lo(rr.z), bf_hi(rr.z)} + o2; o3 = cw2[k][3] * (f32x2){bf_lo(rr.w), bf_hi(rr.w)} + o3; }
;                 u32x4 w; w.x = cvt_pk_bf16(o0[0], o0[1]); w.y = cvt_pk_bf16(o1[0], o1[1]); w.z = cvt_pk_bf16(o2[0], o2[1]); w.w = cvt_pk_bf16(o3[0], o3[1]);
;                 *(LAS u32x4*)(XC + (tr * 8 + j) * XC_PITCH + cgp * 16) = w;
;             }
; #pragma unroll
;             for (int i = 0; i < NIN; ++i) { const int id = tid + i * NTHREADS;
;                 if (dir == 0) *(LAS u32x4*)(TIN + (id >> 2) * IO_NP + (id & 3) * 16) = inr[i];
;                 else *(LAS u32x4*)(TIN + (id >> 3) * IO_WP + (id & 7) * 16) = inr[i]; }
;             LruTile nxt = cur;
;             if (sc < 8) { nxt = lru_tile(Z, ZC, b, h, dir, sc + 1); lru_load_rows(rows, nxt, tr, cgp);
; #pragma unroll
;                 for (int i = 0; i < NIN; ++i) { const int id = tid + i * NTHREADS;
;                     if (dir == 0) inr[i] = *(const u32x4*)(Zg + (size_t)(nxt.t0 + (id >> 2)) * 128 + (id & 3) * 8);
;                     else inr[i] = *(const u32x4*)(Hg + (size_t)(nxt.t0 + (id >> 3)) * DM + (id & 7) * 4); } }
	v_pk_fma_f32 v[162:163], v[46:47], v[242:243], v[162:163]
	v_pk_fma_f32 v[146:147], v[38:39], v[230:231], v[146:147]
	v_cvt_pk_bf16_f32 v224, v66, v67
	v_pk_fma_f32 v[66:67], v[60:61], v[236:237], v[132:133]
	v_cvt_pk_bf16_f32 v225, v146, v147
	v_cvt_pk_bf16_f32 v226, v148, v149
	v_pk_fma_f32 v[148:149], v[52:53], v[240:241], v[128:129]
	v_pk_fma_f32 v[162:163], v[42:43], v[250:251], v[162:163]
	v_lshlrev_b32_e32 v234, 16, v99
	v_and_b32_e32 v235, 0xffff0000, v99
	v_pk_fma_f32 v[146:147], v[62:63], v[238:239], v[134:135]
	v_pk_fma_f32 v[66:67], v[56:57], v[244:245], v[66:67]
	v_pk_fma_f32 v[148:149], v[44:45], v[248:249], v[148:149]
	v_pk_fma_f32 v[162:163], v[34:35], v[234:235], v[162:163]
	v_pk_fma_f32 v[146:147], v[58:59], v[246:247], v[146:147]
	v_pk_fma_f32 v[66:67], v[48:49], v[228:229], v[66:67]
	v_pk_fma_f32 v[148:149], v[40:41], v[232:233], v[148:149]
	v_lshlrev_b32_e32 v236, 16, v100
	v_and_b32_e32 v237, 0xffff0000, v100
	v_lshlrev_b32_e32 v240, 16, v102
	v_and_b32_e32 v241, 0xffff0000, v102
	v_cvt_pk_bf16_f32 v227, v162, v163
	v_pk_fma_f32 v[162:163], v[54:55], v[242:243], v[130:131]
	v_pk_fma_f32 v[146:147], v[50:51], v[230:231], v[146:147]
	v_pk_fma_f32 v[66:67], v[36:37], v[236:237], v[66:67]
	v_lshlrev_b32_e32 v238, 16, v101
	v_and_b32_e32 v239, 0xffff0000, v101
	v_pk_fma_f32 v[148:149], v[32:33], v[240:241], v[148:149]
	s_and_b64 s[18:19], s[18:19], s[20:21]
	ds_write_b128 v166, v[224:227] offset:1088
	v_pk_fma_f32 v[162:163], v[46:47], v[250:251], v[162:163]
	v_pk_fma_f32 v[146:147], v[38:39], v[238:239], v[146:147]
	v_cvt_pk_bf16_f32 v224, v66, v67
	v_pk_fma_f32 v[66:67], v[60:61], v[244:245], v[132:133]
	v_cvt_pk_bf16_f32 v225, v146, v147
	v_cvt_pk_bf16_f32 v226, v148, v149
	v_pk_fma_f32 v[148:149], v[52:53], v[248:249], v[128:129]
	v_pk_fma_f32 v[60:61], v[60:61], v[228:229], v[132:133]
	v_pk_fma_f32 v[52:53], v[52:53], v[232:233], v[128:129]
	s_waitcnt vmcnt(0)
	v_cndmask_b32_e64 v108, 0, v108, s[18:19]
	v_pk_fma_f32 v[162:163], v[42:43], v[234:235], v[162:163]
	v_lshlrev_b32_e32 v242, 16, v103
	v_and_b32_e32 v243, 0xffff0000, v103
	v_pk_fma_f32 v[146:147], v[62:63], v[246:247], v[134:135]
	v_pk_fma_f32 v[66:67], v[56:57], v[228:229], v[66:67]
	v_pk_fma_f32 v[148:149], v[44:45], v[232:233], v[148:149]
	v_lshlrev_b32_e32 v244, 16, v104
	v_and_b32_e32 v245, 0xffff0000, v104
	v_lshlrev_b32_e32 v248, 16, v106
	v_and_b32_e32 v249, 0xffff0000, v106
	v_pk_fma_f32 v[62:63], v[62:63], v[230:231], v[134:135]
	v_pk_fma_f32 v[56:57], v[56:57], v[236:237], v[60:61]
	v_pk_fma_f32 v[44:45], v[44:45], v[240:241], v[52:53]
	v_cndmask_b32_e64 v109, 0, v109, s[18:19]
	v_pk_fma_f32 v[162:163], v[34:35], v[242:243], v[162:163]
	v_pk_fma_f32 v[146:147], v[58:59], v[230:231], v[146:147]
	v_pk_fma_f32 v[66:67], v[48:49], v[236:237], v[66:67]
	v_pk_fma_f32 v[148:149], v[40:41], v[240:241], v[148:149]
	v_lshlrev_b32_e32 v246, 16, v105
	v_and_b32_e32 v247, 0xffff0000, v105
	v_pk_fma_f32 v[58:59], v[58:59], v[238:239], v[62:63]
	v_pk_fma_f32 v[48:49], v[48:49], v[244:245], v[56:57]
	v_pk_fma_f32 v[40:41], v[40:41], v[248:249], v[44:45]
	v_lshlrev_b32_e32 v44, 16, v108
	v_and_b32_e32 v45, 0xffff0000, v108
	v_cndmask_b32_e64 v110, 0, v110, s[18:19]
	v_cvt_pk_bf16_f32 v227, v162, v163
	v_pk_fma_f32 v[162:163], v[54:55], v[250:251], v[130:131]
	v_pk_fma_f32 v[146:147], v[50:51], v[238:239], v[146:147]
	v_pk_fma_f32 v[66:67], v[36:37], v[244:245], v[66:67]
	v_pk_fma_f32 v[54:55], v[54:55], v[234:235], v[130:131]
	v_pk_fma_f32 v[50:51], v[50:51], v[246:247], v[58:59]
	v_pk_fma_f32 v[36:37], v[36:37], v[44:45], v[48:49]
	v_lshlrev_b32_e32 v44, 16, v109
	v_and_b32_e32 v45, 0xffff0000, v109
	v_cndmask_b32_e64 v111, 0, v111, s[18:19]
	v_pk_fma_f32 v[162:163], v[46:47], v[234:235], v[162:163]
	v_pk_fma_f32 v[146:147], v[38:39], v[246:247], v[146:147]
	v_lshlrev_b32_e32 v250, 16, v107
	v_and_b32_e32 v251, 0xffff0000, v107
	v_pk_fma_f32 v[46:47], v[46:47], v[242:243], v[54:55]
	v_pk_fma_f32 v[38:39], v[38:39], v[44:45], v[50:51]
	v_lshlrev_b32_e32 v44, 16, v110
	v_and_b32_e32 v45, 0xffff0000, v110
	v_pk_fma_f32 v[162:163], v[42:43], v[242:243], v[162:163]
	v_pk_fma_f32 v[148:149], v[32:33], v[248:249], v[148:149]
	v_pk_fma_f32 v[42:43], v[42:43], v[250:251], v[46:47]
	v_pk_fma_f32 v[40:41], v[32:33], v[44:45], v[40:41]
	v_lshlrev_b32_e32 v32, 16, v111
	v_and_b32_e32 v33, 0xffff0000, v111
	ds_write_b128 v166, v[224:227] offset:1360
	v_pk_fma_f32 v[162:163], v[34:35], v[250:251], v[162:163]
	v_cvt_pk_bf16_f32 v224, v66, v67
	v_cvt_pk_bf16_f32 v225, v146, v147
	v_cvt_pk_bf16_f32 v226, v148, v149
	v_pk_fma_f32 v[42:43], v[34:35], v[32:33], v[42:43]
	v_cvt_pk_bf16_f32 v227, v162, v163
	ds_write_b128 v166, v[224:227] offset:1632
	v_cvt_pk_bf16_f32 v32, v36, v37
	v_cvt_pk_bf16_f32 v33, v38, v39
	v_cvt_pk_bf16_f32 v34, v40, v41
	v_cvt_pk_bf16_f32 v35, v42, v43
	s_cmp_eq_u32 s44, 0xff800000
	ds_write_b128 v166, v[32:35] offset:1904
	s_branch .Lpc_joinA
.Lpc_newA:
	s_waitcnt vmcnt(0)
	ds_write_b128 v166, v[68:71]
	ds_write_b128 v166, v[72:75] offset:272
	ds_write_b128 v166, v[76:79] offset:544
	ds_write_b128 v166, v[80:83] offset:816
	ds_write_b128 v166, v[84:87] offset:1088
	ds_write_b128 v166, v[88:91] offset:1360
	ds_write_b128 v166, v[92:95] offset:1632
	ds_write_b128 v166, v[96:99] offset:1904
	s_cmp_eq_u32 s44, 0xff800000
.Lpc_joinA:
	ds_write_b128 v168, v[112:115]
	ds_write_b128 v169, v[116:119]
	ds_write_b128 v170, v[120:123]
	ds_write_b128 v171, v[124:127]
	s_cbranch_scc1 .LBB0_308
	v_lshl_add_u64 v[32:33], v[144:145], 0, s[40:41]
	global_load_dwordx4 v[68:71], v[32:33], off offset:-1024 sc1
	global_load_dwordx4 v[72:75], v[32:33], off offset:-768 sc1
	global_load_dwordx4 v[76:79], v[32:33], off offset:-512 sc1
	global_load_dwordx4 v[80:83], v[32:33], off offset:-256 sc1
	global_load_dwordx4 v[84:87], v[32:33], off sc1
	global_load_dwordx4 v[88:91], v[32:33], off offset:256 sc1
	global_load_dwordx4 v[92:95], v[32:33], off offset:512 sc1
	global_load_dwordx4 v[96:99], v[32:33], off offset:768 sc1
	v_lshl_add_u64 v[32:33], v[142:143], 0, s[44:45]
	v_lshl_add_u64 v[34:35], v[252:253], 0, s[44:45]
	global_load_dwordx4 v[112:115], v[32:33], off sc1
	global_load_dwordx4 v[116:119], v[34:35], off sc1
	v_lshl_add_u64 v[32:33], v[154:155], 0, s[44:45]
	v_lshl_add_u64 v[34:35], v[150:151], 0, s[44:45]
	global_load_dwordx4 v[120:123], v[32:33], off sc1
	global_load_dwordx4 v[124:127], v[34:35], off sc1
	s_movk_i32 s28, 0x800
	s_mov_b32 s20, s25
	s_branch .LBB0_309
